# hyena filter generator stage 3 on f32 MFMA (v_mfma_f32_16x16x4_f32) instead of VALU pk_fma with LDS broadcast reads; prep item schedule rebalanced for the cheaper filter item
# speedup vs baseline: 1.1673x; 1.0104x over previous
.LBB0_777:
	s_cmpk_lt_i32 s73, 0x110
	s_cbranch_scc0 .Lps_gen
	s_movk_i32 s101, 0x110
	s_cmpk_lt_i32 s15, 0x112
	s_cselect_b32 s101, 0x4a0, s101
	s_movk_i32 s0, 0x791
	s_branch .Lps_adv
.Lps_gen:
	s_sub_i32 s1, s73, 0x110
	s_cmpk_lt_i32 s1, 0x90
	s_cbranch_scc0 .Lps_gen2
	s_movk_i32 s101, 0x90
	s_cmpk_lt_i32 s15, 0x202
	s_cselect_b32 s101, 0xf0, s101
	s_cmp_lt_i32 s15, 2
	s_cselect_b32 s101, 0x112, s101
	s_movk_i32 s0, 0x321
	s_branch .Lps_adv
.Lps_gen2:
	s_movk_i32 s101, 0x60
	s_cmpk_lt_i32 s15, 0x202
	s_cselect_b32 s101, 0x180, s101
	s_movk_i32 s0, 0x4a1
.Lps_adv:
	s_add_i32 s15, s15, s101
	s_sub_i32 s14, s14, s101
	s_mul_i32 s1, s101, 0x3a20
	s_add_u32 s2, s2, s1
	s_mul_hi_i32 s1, s101, 0x3a20
	s_addc_u32 s3, s3, s1
	s_cmp_gt_i32 s15, s0
	s_cbranch_scc1 .LBB0_763

.LBB0_810:
	v_mov_b32_e32 v13, s26
	v_and_b32_e32 v2, 15, v207
	v_lshrrev_b32_e32 v3, 4, v207
	v_lshrrev_b32_e32 v205, 6, v175
	v_lshlrev_b32_e32 v4, 8, v2
	v_lshl_add_u32 v4, v3, 2, v4
	ds_read_b32 v14, v4 offset:4096
	ds_read_b32 v15, v4 offset:4112
	ds_read_b32 v16, v4 offset:4128
	ds_read_b32 v17, v4 offset:4144
	ds_read_b32 v18, v4 offset:4160
	ds_read_b32 v19, v4 offset:4176
	ds_read_b32 v20, v4 offset:4192
	ds_read_b32 v21, v4 offset:4208
	ds_read_b32 v22, v4 offset:4224
	ds_read_b32 v23, v4 offset:4240
	ds_read_b32 v24, v4 offset:4256
	ds_read_b32 v25, v4 offset:4272
	ds_read_b32 v26, v4 offset:4288
	ds_read_b32 v27, v4 offset:4304
	ds_read_b32 v28, v4 offset:4320
	ds_read_b32 v29, v4 offset:4336
	v_lshlrev_b32_e32 v5, 12, v3
	v_lshl_add_u32 v5, v2, 4, v5
	v_lshl_add_u32 v5, v205, 10, v5
	s_mov_b32 s4, s40
	s_mov_b32 s5, s41
	v_mov_b32_e32 v160, 0
	v_mov_b32_e32 v161, 0
	v_mov_b32_e32 v162, 0
	v_mov_b32_e32 v163, 0
	v_mov_b32_e32 v164, 0
	v_mov_b32_e32 v165, 0
	v_mov_b32_e32 v166, 0
	v_mov_b32_e32 v167, 0
	v_mov_b32_e32 v168, 0
	v_mov_b32_e32 v169, 0
	v_mov_b32_e32 v170, 0
	v_mov_b32_e32 v171, 0
	v_mov_b32_e32 v176, 0
	v_mov_b32_e32 v177, 0
	v_mov_b32_e32 v178, 0
	v_mov_b32_e32 v179, 0
	v_mov_b32_e32 v180, 0
	v_mov_b32_e32 v181, 0
	v_mov_b32_e32 v182, 0
	v_mov_b32_e32 v183, 0
	v_mov_b32_e32 v184, 0
	v_mov_b32_e32 v185, 0
	v_mov_b32_e32 v186, 0
	v_mov_b32_e32 v187, 0
	v_mov_b32_e32 v188, 0
	v_mov_b32_e32 v189, 0
	v_mov_b32_e32 v190, 0
	v_mov_b32_e32 v191, 0
	v_mov_b32_e32 v192, 0
	v_mov_b32_e32 v193, 0
	v_mov_b32_e32 v194, 0
	v_mov_b32_e32 v195, 0
	v_mov_b32_e32 v196, 0
	v_mov_b32_e32 v197, 0
	v_mov_b32_e32 v198, 0
	v_mov_b32_e32 v199, 0
	v_mov_b32_e32 v200, 0
	v_mov_b32_e32 v201, 0
	v_mov_b32_e32 v202, 0
	v_mov_b32_e32 v203, 0
	v_mov_b32_e32 v208, 0
	v_mov_b32_e32 v209, 0
	v_mov_b32_e32 v210, 0
	v_mov_b32_e32 v211, 0
	v_mov_b32_e32 v212, 0
	v_mov_b32_e32 v213, 0
	v_mov_b32_e32 v214, 0
	v_mov_b32_e32 v215, 0
	v_mov_b32_e32 v216, 0
	v_mov_b32_e32 v217, 0
	v_mov_b32_e32 v218, 0
	v_mov_b32_e32 v219, 0
	v_mov_b32_e32 v220, 0
	v_mov_b32_e32 v221, 0
	v_mov_b32_e32 v222, 0
	v_mov_b32_e32 v223, 0
	v_mov_b32_e32 v224, 0
	v_mov_b32_e32 v225, 0
	v_mov_b32_e32 v226, 0
	v_mov_b32_e32 v227, 0
	v_mov_b32_e32 v228, 0
	v_mov_b32_e32 v229, 0
	v_mov_b32_e32 v230, 0
	v_mov_b32_e32 v231, 0
	global_load_dwordx4 v[30:33], v5, s[4:5]
	global_load_dwordx4 v[34:37], v5, s[4:5] offset:256
	global_load_dwordx4 v[38:41], v5, s[4:5] offset:512
	global_load_dwordx4 v[42:45], v5, s[4:5] offset:768
	s_add_u32 s4, s4, 0x4000
	s_addc_u32 s5, s5, 0
	s_waitcnt lgkmcnt(0)
	global_load_dwordx4 v[132:135], v5, s[4:5]
	global_load_dwordx4 v[136:139], v5, s[4:5] offset:256
	global_load_dwordx4 v[140:143], v5, s[4:5] offset:512
	global_load_dwordx4 v[144:147], v5, s[4:5] offset:768
	s_add_u32 s4, s4, 0x4000
	s_addc_u32 s5, s5, 0
	s_waitcnt vmcnt(4)
	v_mfma_f32_16x16x4_f32 v[160:163], v14, v30, v[160:163]
	v_mfma_f32_16x16x4_f32 v[164:167], v14, v31, v[164:167]
	v_mfma_f32_16x16x4_f32 v[168:171], v14, v32, v[168:171]
	v_mfma_f32_16x16x4_f32 v[176:179], v14, v33, v[176:179]
	v_mfma_f32_16x16x4_f32 v[180:183], v14, v34, v[180:183]
	v_mfma_f32_16x16x4_f32 v[184:187], v14, v35, v[184:187]
	v_mfma_f32_16x16x4_f32 v[188:191], v14, v36, v[188:191]
	v_mfma_f32_16x16x4_f32 v[192:195], v14, v37, v[192:195]
	v_mfma_f32_16x16x4_f32 v[196:199], v14, v38, v[196:199]
	v_mfma_f32_16x16x4_f32 v[200:203], v14, v39, v[200:203]
	v_mfma_f32_16x16x4_f32 v[208:211], v14, v40, v[208:211]
	v_mfma_f32_16x16x4_f32 v[212:215], v14, v41, v[212:215]
	v_mfma_f32_16x16x4_f32 v[216:219], v14, v42, v[216:219]
	v_mfma_f32_16x16x4_f32 v[220:223], v14, v43, v[220:223]
	v_mfma_f32_16x16x4_f32 v[224:227], v14, v44, v[224:227]
	v_mfma_f32_16x16x4_f32 v[228:231], v14, v45, v[228:231]
	global_load_dwordx4 v[30:33], v5, s[4:5]
	global_load_dwordx4 v[34:37], v5, s[4:5] offset:256
	global_load_dwordx4 v[38:41], v5, s[4:5] offset:512
	global_load_dwordx4 v[42:45], v5, s[4:5] offset:768
	s_add_u32 s4, s4, 0x4000
	s_addc_u32 s5, s5, 0
	s_waitcnt vmcnt(4)
	v_mfma_f32_16x16x4_f32 v[160:163], v15, v132, v[160:163]
	v_mfma_f32_16x16x4_f32 v[164:167], v15, v133, v[164:167]
	v_mfma_f32_16x16x4_f32 v[168:171], v15, v134, v[168:171]
	v_mfma_f32_16x16x4_f32 v[176:179], v15, v135, v[176:179]
	v_mfma_f32_16x16x4_f32 v[180:183], v15, v136, v[180:183]
	v_mfma_f32_16x16x4_f32 v[184:187], v15, v137, v[184:187]
	v_mfma_f32_16x16x4_f32 v[188:191], v15, v138, v[188:191]
	v_mfma_f32_16x16x4_f32 v[192:195], v15, v139, v[192:195]
	v_mfma_f32_16x16x4_f32 v[196:199], v15, v140, v[196:199]
	v_mfma_f32_16x16x4_f32 v[200:203], v15, v141, v[200:203]
	v_mfma_f32_16x16x4_f32 v[208:211], v15, v142, v[208:211]
	v_mfma_f32_16x16x4_f32 v[212:215], v15, v143, v[212:215]
	v_mfma_f32_16x16x4_f32 v[216:219], v15, v144, v[216:219]
	v_mfma_f32_16x16x4_f32 v[220:223], v15, v145, v[220:223]
	v_mfma_f32_16x16x4_f32 v[224:227], v15, v146, v[224:227]
	v_mfma_f32_16x16x4_f32 v[228:231], v15, v147, v[228:231]
	global_load_dwordx4 v[132:135], v5, s[4:5]
	global_load_dwordx4 v[136:139], v5, s[4:5] offset:256
	global_load_dwordx4 v[140:143], v5, s[4:5] offset:512
	global_load_dwordx4 v[144:147], v5, s[4:5] offset:768
	s_add_u32 s4, s4, 0x4000
	s_addc_u32 s5, s5, 0
	s_waitcnt vmcnt(4)
	v_mfma_f32_16x16x4_f32 v[160:163], v16, v30, v[160:163]
	v_mfma_f32_16x16x4_f32 v[164:167], v16, v31, v[164:167]
	v_mfma_f32_16x16x4_f32 v[168:171], v16, v32, v[168:171]
	v_mfma_f32_16x16x4_f32 v[176:179], v16, v33, v[176:179]
	v_mfma_f32_16x16x4_f32 v[180:183], v16, v34, v[180:183]
	v_mfma_f32_16x16x4_f32 v[184:187], v16, v35, v[184:187]
	v_mfma_f32_16x16x4_f32 v[188:191], v16, v36, v[188:191]
	v_mfma_f32_16x16x4_f32 v[192:195], v16, v37, v[192:195]
	v_mfma_f32_16x16x4_f32 v[196:199], v16, v38, v[196:199]
	v_mfma_f32_16x16x4_f32 v[200:203], v16, v39, v[200:203]
	v_mfma_f32_16x16x4_f32 v[208:211], v16, v40, v[208:211]
	v_mfma_f32_16x16x4_f32 v[212:215], v16, v41, v[212:215]
	v_mfma_f32_16x16x4_f32 v[216:219], v16, v42, v[216:219]
	v_mfma_f32_16x16x4_f32 v[220:223], v16, v43, v[220:223]
	v_mfma_f32_16x16x4_f32 v[224:227], v16, v44, v[224:227]
	v_mfma_f32_16x16x4_f32 v[228:231], v16, v45, v[228:231]
	global_load_dwordx4 v[30:33], v5, s[4:5]
	global_load_dwordx4 v[34:37], v5, s[4:5] offset:256
	global_load_dwordx4 v[38:41], v5, s[4:5] offset:512
	global_load_dwordx4 v[42:45], v5, s[4:5] offset:768
	s_add_u32 s4, s4, 0x4000
	s_addc_u32 s5, s5, 0
	s_waitcnt vmcnt(4)
	v_mfma_f32_16x16x4_f32 v[160:163], v17, v132, v[160:163]
	v_mfma_f32_16x16x4_f32 v[164:167], v17, v133, v[164:167]
	v_mfma_f32_16x16x4_f32 v[168:171], v17, v134, v[168:171]
	v_mfma_f32_16x16x4_f32 v[176:179], v17, v135, v[176:179]
	v_mfma_f32_16x16x4_f32 v[180:183], v17, v136, v[180:183]
	v_mfma_f32_16x16x4_f32 v[184:187], v17, v137, v[184:187]
	v_mfma_f32_16x16x4_f32 v[188:191], v17, v138, v[188:191]
	v_mfma_f32_16x16x4_f32 v[192:195], v17, v139, v[192:195]
	v_mfma_f32_16x16x4_f32 v[196:199], v17, v140, v[196:199]
	v_mfma_f32_16x16x4_f32 v[200:203], v17, v141, v[200:203]
	v_mfma_f32_16x16x4_f32 v[208:211], v17, v142, v[208:211]
	v_mfma_f32_16x16x4_f32 v[212:215], v17, v143, v[212:215]
	v_mfma_f32_16x16x4_f32 v[216:219], v17, v144, v[216:219]
	v_mfma_f32_16x16x4_f32 v[220:223], v17, v145, v[220:223]
	v_mfma_f32_16x16x4_f32 v[224:227], v17, v146, v[224:227]
	v_mfma_f32_16x16x4_f32 v[228:231], v17, v147, v[228:231]
	global_load_dwordx4 v[132:135], v5, s[4:5]
	global_load_dwordx4 v[136:139], v5, s[4:5] offset:256
	global_load_dwordx4 v[140:143], v5, s[4:5] offset:512
	global_load_dwordx4 v[144:147], v5, s[4:5] offset:768
	s_add_u32 s4, s4, 0x4000
	s_addc_u32 s5, s5, 0
	s_waitcnt vmcnt(4)
	v_mfma_f32_16x16x4_f32 v[160:163], v18, v30, v[160:163]
	v_mfma_f32_16x16x4_f32 v[164:167], v18, v31, v[164:167]
	v_mfma_f32_16x16x4_f32 v[168:171], v18, v32, v[168:171]
	v_mfma_f32_16x16x4_f32 v[176:179], v18, v33, v[176:179]
	v_mfma_f32_16x16x4_f32 v[180:183], v18, v34, v[180:183]
	v_mfma_f32_16x16x4_f32 v[184:187], v18, v35, v[184:187]
	v_mfma_f32_16x16x4_f32 v[188:191], v18, v36, v[188:191]
	v_mfma_f32_16x16x4_f32 v[192:195], v18, v37, v[192:195]
	v_mfma_f32_16x16x4_f32 v[196:199], v18, v38, v[196:199]
	v_mfma_f32_16x16x4_f32 v[200:203], v18, v39, v[200:203]
	v_mfma_f32_16x16x4_f32 v[208:211], v18, v40, v[208:211]
	v_mfma_f32_16x16x4_f32 v[212:215], v18, v41, v[212:215]
	v_mfma_f32_16x16x4_f32 v[216:219], v18, v42, v[216:219]
	v_mfma_f32_16x16x4_f32 v[220:223], v18, v43, v[220:223]
	v_mfma_f32_16x16x4_f32 v[224:227], v18, v44, v[224:227]
	v_mfma_f32_16x16x4_f32 v[228:231], v18, v45, v[228:231]
	global_load_dwordx4 v[30:33], v5, s[4:5]
	global_load_dwordx4 v[34:37], v5, s[4:5] offset:256
	global_load_dwordx4 v[38:41], v5, s[4:5] offset:512
	global_load_dwordx4 v[42:45], v5, s[4:5] offset:768
	s_add_u32 s4, s4, 0x4000
	s_addc_u32 s5, s5, 0
	s_waitcnt vmcnt(4)
	v_mfma_f32_16x16x4_f32 v[160:163], v19, v132, v[160:163]
	v_mfma_f32_16x16x4_f32 v[164:167], v19, v133, v[164:167]
	v_mfma_f32_16x16x4_f32 v[168:171], v19, v134, v[168:171]
	v_mfma_f32_16x16x4_f32 v[176:179], v19, v135, v[176:179]
	v_mfma_f32_16x16x4_f32 v[180:183], v19, v136, v[180:183]
	v_mfma_f32_16x16x4_f32 v[184:187], v19, v137, v[184:187]
	v_mfma_f32_16x16x4_f32 v[188:191], v19, v138, v[188:191]
	v_mfma_f32_16x16x4_f32 v[192:195], v19, v139, v[192:195]
	v_mfma_f32_16x16x4_f32 v[196:199], v19, v140, v[196:199]
	v_mfma_f32_16x16x4_f32 v[200:203], v19, v141, v[200:203]
	v_mfma_f32_16x16x4_f32 v[208:211], v19, v142, v[208:211]
	v_mfma_f32_16x16x4_f32 v[212:215], v19, v143, v[212:215]
	v_mfma_f32_16x16x4_f32 v[216:219], v19, v144, v[216:219]
	v_mfma_f32_16x16x4_f32 v[220:223], v19, v145, v[220:223]
	v_mfma_f32_16x16x4_f32 v[224:227], v19, v146, v[224:227]
	v_mfma_f32_16x16x4_f32 v[228:231], v19, v147, v[228:231]
	global_load_dwordx4 v[132:135], v5, s[4:5]
	global_load_dwordx4 v[136:139], v5, s[4:5] offset:256
	global_load_dwordx4 v[140:143], v5, s[4:5] offset:512
	global_load_dwordx4 v[144:147], v5, s[4:5] offset:768
	s_add_u32 s4, s4, 0x4000
	s_addc_u32 s5, s5, 0
	s_waitcnt vmcnt(4)
	v_mfma_f32_16x16x4_f32 v[160:163], v20, v30, v[160:163]
	v_mfma_f32_16x16x4_f32 v[164:167], v20, v31, v[164:167]
	v_mfma_f32_16x16x4_f32 v[168:171], v20, v32, v[168:171]
	v_mfma_f32_16x16x4_f32 v[176:179], v20, v33, v[176:179]
	v_mfma_f32_16x16x4_f32 v[180:183], v20, v34, v[180:183]
	v_mfma_f32_16x16x4_f32 v[184:187], v20, v35, v[184:187]
	v_mfma_f32_16x16x4_f32 v[188:191], v20, v36, v[188:191]
	v_mfma_f32_16x16x4_f32 v[192:195], v20, v37, v[192:195]
	v_mfma_f32_16x16x4_f32 v[196:199], v20, v38, v[196:199]
	v_mfma_f32_16x16x4_f32 v[200:203], v20, v39, v[200:203]
	v_mfma_f32_16x16x4_f32 v[208:211], v20, v40, v[208:211]
	v_mfma_f32_16x16x4_f32 v[212:215], v20, v41, v[212:215]
	v_mfma_f32_16x16x4_f32 v[216:219], v20, v42, v[216:219]
	v_mfma_f32_16x16x4_f32 v[220:223], v20, v43, v[220:223]
	v_mfma_f32_16x16x4_f32 v[224:227], v20, v44, v[224:227]
	v_mfma_f32_16x16x4_f32 v[228:231], v20, v45, v[228:231]
	global_load_dwordx4 v[30:33], v5, s[4:5]
	global_load_dwordx4 v[34:37], v5, s[4:5] offset:256
	global_load_dwordx4 v[38:41], v5, s[4:5] offset:512
	global_load_dwordx4 v[42:45], v5, s[4:5] offset:768
	s_add_u32 s4, s4, 0x4000
	s_addc_u32 s5, s5, 0
	s_waitcnt vmcnt(4)
	v_mfma_f32_16x16x4_f32 v[160:163], v21, v132, v[160:163]
	v_mfma_f32_16x16x4_f32 v[164:167], v21, v133, v[164:167]
	v_mfma_f32_16x16x4_f32 v[168:171], v21, v134, v[168:171]
	v_mfma_f32_16x16x4_f32 v[176:179], v21, v135, v[176:179]
	v_mfma_f32_16x16x4_f32 v[180:183], v21, v136, v[180:183]
	v_mfma_f32_16x16x4_f32 v[184:187], v21, v137, v[184:187]
	v_mfma_f32_16x16x4_f32 v[188:191], v21, v138, v[188:191]
	v_mfma_f32_16x16x4_f32 v[192:195], v21, v139, v[192:195]
	v_mfma_f32_16x16x4_f32 v[196:199], v21, v140, v[196:199]
	v_mfma_f32_16x16x4_f32 v[200:203], v21, v141, v[200:203]
	v_mfma_f32_16x16x4_f32 v[208:211], v21, v142, v[208:211]
	v_mfma_f32_16x16x4_f32 v[212:215], v21, v143, v[212:215]
	v_mfma_f32_16x16x4_f32 v[216:219], v21, v144, v[216:219]
	v_mfma_f32_16x16x4_f32 v[220:223], v21, v145, v[220:223]
	v_mfma_f32_16x16x4_f32 v[224:227], v21, v146, v[224:227]
	v_mfma_f32_16x16x4_f32 v[228:231], v21, v147, v[228:231]
	global_load_dwordx4 v[132:135], v5, s[4:5]
	global_load_dwordx4 v[136:139], v5, s[4:5] offset:256
	global_load_dwordx4 v[140:143], v5, s[4:5] offset:512
	global_load_dwordx4 v[144:147], v5, s[4:5] offset:768
	s_add_u32 s4, s4, 0x4000
	s_addc_u32 s5, s5, 0
	s_waitcnt vmcnt(4)
	v_mfma_f32_16x16x4_f32 v[160:163], v22, v30, v[160:163]
	v_mfma_f32_16x16x4_f32 v[164:167], v22, v31, v[164:167]
	v_mfma_f32_16x16x4_f32 v[168:171], v22, v32, v[168:171]
	v_mfma_f32_16x16x4_f32 v[176:179], v22, v33, v[176:179]
	v_mfma_f32_16x16x4_f32 v[180:183], v22, v34, v[180:183]
	v_mfma_f32_16x16x4_f32 v[184:187], v22, v35, v[184:187]
	v_mfma_f32_16x16x4_f32 v[188:191], v22, v36, v[188:191]
	v_mfma_f32_16x16x4_f32 v[192:195], v22, v37, v[192:195]
	v_mfma_f32_16x16x4_f32 v[196:199], v22, v38, v[196:199]
	v_mfma_f32_16x16x4_f32 v[200:203], v22, v39, v[200:203]
	v_mfma_f32_16x16x4_f32 v[208:211], v22, v40, v[208:211]
	v_mfma_f32_16x16x4_f32 v[212:215], v22, v41, v[212:215]
	v_mfma_f32_16x16x4_f32 v[216:219], v22, v42, v[216:219]
	v_mfma_f32_16x16x4_f32 v[220:223], v22, v43, v[220:223]
	v_mfma_f32_16x16x4_f32 v[224:227], v22, v44, v[224:227]
	v_mfma_f32_16x16x4_f32 v[228:231], v22, v45, v[228:231]
	global_load_dwordx4 v[30:33], v5, s[4:5]
	global_load_dwordx4 v[34:37], v5, s[4:5] offset:256
	global_load_dwordx4 v[38:41], v5, s[4:5] offset:512
	global_load_dwordx4 v[42:45], v5, s[4:5] offset:768
	s_add_u32 s4, s4, 0x4000
	s_addc_u32 s5, s5, 0
	s_waitcnt vmcnt(4)
	v_mfma_f32_16x16x4_f32 v[160:163], v23, v132, v[160:163]
	v_mfma_f32_16x16x4_f32 v[164:167], v23, v133, v[164:167]
	v_mfma_f32_16x16x4_f32 v[168:171], v23, v134, v[168:171]
	v_mfma_f32_16x16x4_f32 v[176:179], v23, v135, v[176:179]
	v_mfma_f32_16x16x4_f32 v[180:183], v23, v136, v[180:183]
	v_mfma_f32_16x16x4_f32 v[184:187], v23, v137, v[184:187]
	v_mfma_f32_16x16x4_f32 v[188:191], v23, v138, v[188:191]
	v_mfma_f32_16x16x4_f32 v[192:195], v23, v139, v[192:195]
	v_mfma_f32_16x16x4_f32 v[196:199], v23, v140, v[196:199]
	v_mfma_f32_16x16x4_f32 v[200:203], v23, v141, v[200:203]
	v_mfma_f32_16x16x4_f32 v[208:211], v23, v142, v[208:211]
	v_mfma_f32_16x16x4_f32 v[212:215], v23, v143, v[212:215]
	v_mfma_f32_16x16x4_f32 v[216:219], v23, v144, v[216:219]
	v_mfma_f32_16x16x4_f32 v[220:223], v23, v145, v[220:223]
	v_mfma_f32_16x16x4_f32 v[224:227], v23, v146, v[224:227]
	v_mfma_f32_16x16x4_f32 v[228:231], v23, v147, v[228:231]
	global_load_dwordx4 v[132:135], v5, s[4:5]
	global_load_dwordx4 v[136:139], v5, s[4:5] offset:256
	global_load_dwordx4 v[140:143], v5, s[4:5] offset:512
	global_load_dwordx4 v[144:147], v5, s[4:5] offset:768
	s_add_u32 s4, s4, 0x4000
	s_addc_u32 s5, s5, 0
	s_waitcnt vmcnt(4)
	v_mfma_f32_16x16x4_f32 v[160:163], v24, v30, v[160:163]
	v_mfma_f32_16x16x4_f32 v[164:167], v24, v31, v[164:167]
	v_mfma_f32_16x16x4_f32 v[168:171], v24, v32, v[168:171]
	v_mfma_f32_16x16x4_f32 v[176:179], v24, v33, v[176:179]
	v_mfma_f32_16x16x4_f32 v[180:183], v24, v34, v[180:183]
	v_mfma_f32_16x16x4_f32 v[184:187], v24, v35, v[184:187]
	v_mfma_f32_16x16x4_f32 v[188:191], v24, v36, v[188:191]
	v_mfma_f32_16x16x4_f32 v[192:195], v24, v37, v[192:195]
	v_mfma_f32_16x16x4_f32 v[196:199], v24, v38, v[196:199]
	v_mfma_f32_16x16x4_f32 v[200:203], v24, v39, v[200:203]
	v_mfma_f32_16x16x4_f32 v[208:211], v24, v40, v[208:211]
	v_mfma_f32_16x16x4_f32 v[212:215], v24, v41, v[212:215]
	v_mfma_f32_16x16x4_f32 v[216:219], v24, v42, v[216:219]
	v_mfma_f32_16x16x4_f32 v[220:223], v24, v43, v[220:223]
	v_mfma_f32_16x16x4_f32 v[224:227], v24, v44, v[224:227]
	v_mfma_f32_16x16x4_f32 v[228:231], v24, v45, v[228:231]
	global_load_dwordx4 v[30:33], v5, s[4:5]
	global_load_dwordx4 v[34:37], v5, s[4:5] offset:256
	global_load_dwordx4 v[38:41], v5, s[4:5] offset:512
	global_load_dwordx4 v[42:45], v5, s[4:5] offset:768
	s_add_u32 s4, s4, 0x4000
	s_addc_u32 s5, s5, 0
	s_waitcnt vmcnt(4)
	v_mfma_f32_16x16x4_f32 v[160:163], v25, v132, v[160:163]
	v_mfma_f32_16x16x4_f32 v[164:167], v25, v133, v[164:167]
	v_mfma_f32_16x16x4_f32 v[168:171], v25, v134, v[168:171]
	v_mfma_f32_16x16x4_f32 v[176:179], v25, v135, v[176:179]
	v_mfma_f32_16x16x4_f32 v[180:183], v25, v136, v[180:183]
	v_mfma_f32_16x16x4_f32 v[184:187], v25, v137, v[184:187]
	v_mfma_f32_16x16x4_f32 v[188:191], v25, v138, v[188:191]
	v_mfma_f32_16x16x4_f32 v[192:195], v25, v139, v[192:195]
	v_mfma_f32_16x16x4_f32 v[196:199], v25, v140, v[196:199]
	v_mfma_f32_16x16x4_f32 v[200:203], v25, v141, v[200:203]
	v_mfma_f32_16x16x4_f32 v[208:211], v25, v142, v[208:211]
	v_mfma_f32_16x16x4_f32 v[212:215], v25, v143, v[212:215]
	v_mfma_f32_16x16x4_f32 v[216:219], v25, v144, v[216:219]
	v_mfma_f32_16x16x4_f32 v[220:223], v25, v145, v[220:223]
	v_mfma_f32_16x16x4_f32 v[224:227], v25, v146, v[224:227]
	v_mfma_f32_16x16x4_f32 v[228:231], v25, v147, v[228:231]
	global_load_dwordx4 v[132:135], v5, s[4:5]
	global_load_dwordx4 v[136:139], v5, s[4:5] offset:256
	global_load_dwordx4 v[140:143], v5, s[4:5] offset:512
	global_load_dwordx4 v[144:147], v5, s[4:5] offset:768
	s_add_u32 s4, s4, 0x4000
	s_addc_u32 s5, s5, 0
	s_waitcnt vmcnt(4)
	v_mfma_f32_16x16x4_f32 v[160:163], v26, v30, v[160:163]
	v_mfma_f32_16x16x4_f32 v[164:167], v26, v31, v[164:167]
	v_mfma_f32_16x16x4_f32 v[168:171], v26, v32, v[168:171]
	v_mfma_f32_16x16x4_f32 v[176:179], v26, v33, v[176:179]
	v_mfma_f32_16x16x4_f32 v[180:183], v26, v34, v[180:183]
	v_mfma_f32_16x16x4_f32 v[184:187], v26, v35, v[184:187]
	v_mfma_f32_16x16x4_f32 v[188:191], v26, v36, v[188:191]
	v_mfma_f32_16x16x4_f32 v[192:195], v26, v37, v[192:195]
	v_mfma_f32_16x16x4_f32 v[196:199], v26, v38, v[196:199]
	v_mfma_f32_16x16x4_f32 v[200:203], v26, v39, v[200:203]
	v_mfma_f32_16x16x4_f32 v[208:211], v26, v40, v[208:211]
	v_mfma_f32_16x16x4_f32 v[212:215], v26, v41, v[212:215]
	v_mfma_f32_16x16x4_f32 v[216:219], v26, v42, v[216:219]
	v_mfma_f32_16x16x4_f32 v[220:223], v26, v43, v[220:223]
	v_mfma_f32_16x16x4_f32 v[224:227], v26, v44, v[224:227]
	v_mfma_f32_16x16x4_f32 v[228:231], v26, v45, v[228:231]
	global_load_dwordx4 v[30:33], v5, s[4:5]
	global_load_dwordx4 v[34:37], v5, s[4:5] offset:256
	global_load_dwordx4 v[38:41], v5, s[4:5] offset:512
	global_load_dwordx4 v[42:45], v5, s[4:5] offset:768
	s_add_u32 s4, s4, 0x4000
	s_addc_u32 s5, s5, 0
	s_waitcnt vmcnt(4)
	v_mfma_f32_16x16x4_f32 v[160:163], v27, v132, v[160:163]
	v_mfma_f32_16x16x4_f32 v[164:167], v27, v133, v[164:167]
	v_mfma_f32_16x16x4_f32 v[168:171], v27, v134, v[168:171]
	v_mfma_f32_16x16x4_f32 v[176:179], v27, v135, v[176:179]
	v_mfma_f32_16x16x4_f32 v[180:183], v27, v136, v[180:183]
	v_mfma_f32_16x16x4_f32 v[184:187], v27, v137, v[184:187]
	v_mfma_f32_16x16x4_f32 v[188:191], v27, v138, v[188:191]
	v_mfma_f32_16x16x4_f32 v[192:195], v27, v139, v[192:195]
	v_mfma_f32_16x16x4_f32 v[196:199], v27, v140, v[196:199]
	v_mfma_f32_16x16x4_f32 v[200:203], v27, v141, v[200:203]
	v_mfma_f32_16x16x4_f32 v[208:211], v27, v142, v[208:211]
	v_mfma_f32_16x16x4_f32 v[212:215], v27, v143, v[212:215]
	v_mfma_f32_16x16x4_f32 v[216:219], v27, v144, v[216:219]
	v_mfma_f32_16x16x4_f32 v[220:223], v27, v145, v[220:223]
	v_mfma_f32_16x16x4_f32 v[224:227], v27, v146, v[224:227]
	v_mfma_f32_16x16x4_f32 v[228:231], v27, v147, v[228:231]
	global_load_dwordx4 v[132:135], v5, s[4:5]
	global_load_dwordx4 v[136:139], v5, s[4:5] offset:256
	global_load_dwordx4 v[140:143], v5, s[4:5] offset:512
	global_load_dwordx4 v[144:147], v5, s[4:5] offset:768
	s_add_u32 s4, s4, 0x4000
	s_addc_u32 s5, s5, 0
	s_waitcnt vmcnt(4)
	v_mfma_f32_16x16x4_f32 v[160:163], v28, v30, v[160:163]
	v_mfma_f32_16x16x4_f32 v[164:167], v28, v31, v[164:167]
	v_mfma_f32_16x16x4_f32 v[168:171], v28, v32, v[168:171]
	v_mfma_f32_16x16x4_f32 v[176:179], v28, v33, v[176:179]
	v_mfma_f32_16x16x4_f32 v[180:183], v28, v34, v[180:183]
	v_mfma_f32_16x16x4_f32 v[184:187], v28, v35, v[184:187]
	v_mfma_f32_16x16x4_f32 v[188:191], v28, v36, v[188:191]
	v_mfma_f32_16x16x4_f32 v[192:195], v28, v37, v[192:195]
	v_mfma_f32_16x16x4_f32 v[196:199], v28, v38, v[196:199]
	v_mfma_f32_16x16x4_f32 v[200:203], v28, v39, v[200:203]
	v_mfma_f32_16x16x4_f32 v[208:211], v28, v40, v[208:211]
	v_mfma_f32_16x16x4_f32 v[212:215], v28, v41, v[212:215]
	v_mfma_f32_16x16x4_f32 v[216:219], v28, v42, v[216:219]
	v_mfma_f32_16x16x4_f32 v[220:223], v28, v43, v[220:223]
	v_mfma_f32_16x16x4_f32 v[224:227], v28, v44, v[224:227]
	v_mfma_f32_16x16x4_f32 v[228:231], v28, v45, v[228:231]
	s_waitcnt vmcnt(0)
	v_mfma_f32_16x16x4_f32 v[160:163], v29, v132, v[160:163]
	v_mfma_f32_16x16x4_f32 v[164:167], v29, v133, v[164:167]
	v_mfma_f32_16x16x4_f32 v[168:171], v29, v134, v[168:171]
	v_mfma_f32_16x16x4_f32 v[176:179], v29, v135, v[176:179]
	v_mfma_f32_16x16x4_f32 v[180:183], v29, v136, v[180:183]
	v_mfma_f32_16x16x4_f32 v[184:187], v29, v137, v[184:187]
	v_mfma_f32_16x16x4_f32 v[188:191], v29, v138, v[188:191]
	v_mfma_f32_16x16x4_f32 v[192:195], v29, v139, v[192:195]
	v_mfma_f32_16x16x4_f32 v[196:199], v29, v140, v[196:199]
	v_mfma_f32_16x16x4_f32 v[200:203], v29, v141, v[200:203]
	v_mfma_f32_16x16x4_f32 v[208:211], v29, v142, v[208:211]
	v_mfma_f32_16x16x4_f32 v[212:215], v29, v143, v[212:215]
	v_mfma_f32_16x16x4_f32 v[216:219], v29, v144, v[216:219]
	v_mfma_f32_16x16x4_f32 v[220:223], v29, v145, v[220:223]
	v_mfma_f32_16x16x4_f32 v[224:227], v29, v146, v[224:227]
	v_mfma_f32_16x16x4_f32 v[228:231], v29, v147, v[228:231]
	s_nop 7
	s_nop 3
	v_lshl_add_u32 v13, v3, 2, v13
	v_mov_b32_e32 v12, 0xc37f0000
	v_add_u32_e32 v10, 0, v13
	v_cvt_f32_u32_e32 v10, v10
	v_div_scale_f32 v11, vcc, v12, v12, v10
	v_rcp_f32_e32 v148, v11
	s_nop 0
	v_fma_f32 v158, -v11, v148, 1.0
	v_fmac_f32_e32 v148, v158, v148
	v_div_scale_f32 v158, vcc, v10, v12, v10
	v_mul_f32_e32 v159, v158, v148
	v_fma_f32 v172, -v11, v159, v158
	v_fmac_f32_e32 v159, v172, v148
	v_fma_f32 v158, -v11, v159, v158
	v_div_fmas_f32 v158, v158, v148, v159
	v_div_fixup_f32 v6, v158, v12, v10
	v_add_u32_e32 v10, 1, v13
	v_cvt_f32_u32_e32 v10, v10
	v_div_scale_f32 v11, vcc, v12, v12, v10
	v_rcp_f32_e32 v148, v11
	s_nop 0
	v_fma_f32 v158, -v11, v148, 1.0
	v_fmac_f32_e32 v148, v158, v148
	v_div_scale_f32 v158, vcc, v10, v12, v10
	v_mul_f32_e32 v159, v158, v148
	v_fma_f32 v172, -v11, v159, v158
	v_fmac_f32_e32 v159, v172, v148
	v_fma_f32 v158, -v11, v159, v158
	v_div_fmas_f32 v158, v158, v148, v159
	v_div_fixup_f32 v7, v158, v12, v10
	v_add_u32_e32 v10, 2, v13
	v_cvt_f32_u32_e32 v10, v10
	v_div_scale_f32 v11, vcc, v12, v12, v10
	v_rcp_f32_e32 v148, v11
	s_nop 0
	v_fma_f32 v158, -v11, v148, 1.0
	v_fmac_f32_e32 v148, v158, v148
	v_div_scale_f32 v158, vcc, v10, v12, v10
	v_mul_f32_e32 v159, v158, v148
	v_fma_f32 v172, -v11, v159, v158
	v_fmac_f32_e32 v159, v172, v148
	v_fma_f32 v158, -v11, v159, v158
	v_div_fmas_f32 v158, v158, v148, v159
	v_div_fixup_f32 v8, v158, v12, v10
	v_add_u32_e32 v10, 3, v13
	v_cvt_f32_u32_e32 v10, v10
	v_div_scale_f32 v11, vcc, v12, v12, v10
	v_rcp_f32_e32 v148, v11
	s_nop 0
	v_fma_f32 v158, -v11, v148, 1.0
	v_fmac_f32_e32 v148, v158, v148
	v_div_scale_f32 v158, vcc, v10, v12, v10
	v_mul_f32_e32 v159, v158, v148
	v_fma_f32 v172, -v11, v159, v158
	v_fmac_f32_e32 v159, v172, v148
	v_fma_f32 v158, -v11, v159, v158
	v_div_fmas_f32 v158, v158, v148, v159
	v_div_fixup_f32 v9, v158, v12, v10
	v_lshlrev_b32_e32 v10, 8, v205
	v_lshl_add_u32 v10, v2, 2, v10
	v_lshlrev_b32_e32 v11, 10, v10
	v_lshl_add_u32 v11, v3, 4, v11
	v_lshlrev_b32_e32 v10, 2, v2
	v_mov_b32_e32 v173, 0x40447cbd
	v_mov_b32_e32 v148, v10
	v_cvt_f32_u32_e32 v148, v148
	v_fmamk_f32 v148, v148, 0x3d4541ff, v173
	v_mul_f32_e32 v158, v6, v148
	v_mul_f32_e32 v158, 0x3fb8aa3b, v158
	v_exp_f32_e32 v158, v158
	v_mul_f32_e32 v159, v7, v148
	v_mul_f32_e32 v159, 0x3fb8aa3b, v159
	v_exp_f32_e32 v159, v159
	v_mul_f32_e32 v172, v8, v148
	v_mul_f32_e32 v172, 0x3fb8aa3b, v172
	v_exp_f32_e32 v172, v172
	v_mul_f32_e32 v204, v9, v148
	v_mul_f32_e32 v204, 0x3fb8aa3b, v204
	v_exp_f32_e32 v204, v204
	s_nop 0
	v_mul_f32_e32 v160, v158, v160
	v_mul_f32_e32 v161, v159, v161
	v_mul_f32_e32 v162, v172, v162
	v_mul_f32_e32 v163, v204, v163
	global_store_dwordx4 v11, v[160:163], s[0:1]
	v_add_u32_e32 v148, 1, v10
	v_cvt_f32_u32_e32 v148, v148
	v_fmamk_f32 v148, v148, 0x3d4541ff, v173
	v_mul_f32_e32 v158, v6, v148
	v_mul_f32_e32 v158, 0x3fb8aa3b, v158
	v_exp_f32_e32 v158, v158
	v_mul_f32_e32 v159, v7, v148
	v_mul_f32_e32 v159, 0x3fb8aa3b, v159
	v_exp_f32_e32 v159, v159
	v_mul_f32_e32 v172, v8, v148
	v_mul_f32_e32 v172, 0x3fb8aa3b, v172
	v_exp_f32_e32 v172, v172
	v_mul_f32_e32 v204, v9, v148
	v_mul_f32_e32 v204, 0x3fb8aa3b, v204
	v_exp_f32_e32 v204, v204
	s_nop 0
	v_mul_f32_e32 v164, v158, v164
	v_mul_f32_e32 v165, v159, v165
	v_mul_f32_e32 v166, v172, v166
	v_mul_f32_e32 v167, v204, v167
	v_add_u32_e32 v205, 0x400, v11
	global_store_dwordx4 v205, v[164:167], s[0:1]
	v_add_u32_e32 v148, 2, v10
	v_cvt_f32_u32_e32 v148, v148
	v_fmamk_f32 v148, v148, 0x3d4541ff, v173
	v_mul_f32_e32 v158, v6, v148
	v_mul_f32_e32 v158, 0x3fb8aa3b, v158
	v_exp_f32_e32 v158, v158
	v_mul_f32_e32 v159, v7, v148
	v_mul_f32_e32 v159, 0x3fb8aa3b, v159
	v_exp_f32_e32 v159, v159
	v_mul_f32_e32 v172, v8, v148
	v_mul_f32_e32 v172, 0x3fb8aa3b, v172
	v_exp_f32_e32 v172, v172
	v_mul_f32_e32 v204, v9, v148
	v_mul_f32_e32 v204, 0x3fb8aa3b, v204
	v_exp_f32_e32 v204, v204
	s_nop 0
	v_mul_f32_e32 v168, v158, v168
	v_mul_f32_e32 v169, v159, v169
	v_mul_f32_e32 v170, v172, v170
	v_mul_f32_e32 v171, v204, v171
	v_add_u32_e32 v205, 0x800, v11
	global_store_dwordx4 v205, v[168:171], s[0:1]
	v_add_u32_e32 v148, 3, v10
	v_cvt_f32_u32_e32 v148, v148
	v_fmamk_f32 v148, v148, 0x3d4541ff, v173
	v_mul_f32_e32 v158, v6, v148
	v_mul_f32_e32 v158, 0x3fb8aa3b, v158
	v_exp_f32_e32 v158, v158
	v_mul_f32_e32 v159, v7, v148
	v_mul_f32_e32 v159, 0x3fb8aa3b, v159
	v_exp_f32_e32 v159, v159
	v_mul_f32_e32 v172, v8, v148
	v_mul_f32_e32 v172, 0x3fb8aa3b, v172
	v_exp_f32_e32 v172, v172
	v_mul_f32_e32 v204, v9, v148
	v_mul_f32_e32 v204, 0x3fb8aa3b, v204
	v_exp_f32_e32 v204, v204
	s_nop 0
	v_mul_f32_e32 v176, v158, v176
	v_mul_f32_e32 v177, v159, v177
	v_mul_f32_e32 v178, v172, v178
	v_mul_f32_e32 v179, v204, v179
	v_add_u32_e32 v205, 0xc00, v11
	global_store_dwordx4 v205, v[176:179], s[0:1]
	v_add_u32_e32 v148, 64, v10
	v_cvt_f32_u32_e32 v148, v148
	v_fmamk_f32 v148, v148, 0x3d4541ff, v173
	v_mul_f32_e32 v158, v6, v148
	v_mul_f32_e32 v158, 0x3fb8aa3b, v158
	v_exp_f32_e32 v158, v158
	v_mul_f32_e32 v159, v7, v148
	v_mul_f32_e32 v159, 0x3fb8aa3b, v159
	v_exp_f32_e32 v159, v159
	v_mul_f32_e32 v172, v8, v148
	v_mul_f32_e32 v172, 0x3fb8aa3b, v172
	v_exp_f32_e32 v172, v172
	v_mul_f32_e32 v204, v9, v148
	v_mul_f32_e32 v204, 0x3fb8aa3b, v204
	v_exp_f32_e32 v204, v204
	s_nop 0
	v_mul_f32_e32 v180, v158, v180
	v_mul_f32_e32 v181, v159, v181
	v_mul_f32_e32 v182, v172, v182
	v_mul_f32_e32 v183, v204, v183
	v_add_u32_e32 v205, 0x10000, v11
	global_store_dwordx4 v205, v[180:183], s[0:1]
	v_add_u32_e32 v148, 65, v10
	v_cvt_f32_u32_e32 v148, v148
	v_fmamk_f32 v148, v148, 0x3d4541ff, v173
	v_mul_f32_e32 v158, v6, v148
	v_mul_f32_e32 v158, 0x3fb8aa3b, v158
	v_exp_f32_e32 v158, v158
	v_mul_f32_e32 v159, v7, v148
	v_mul_f32_e32 v159, 0x3fb8aa3b, v159
	v_exp_f32_e32 v159, v159
	v_mul_f32_e32 v172, v8, v148
	v_mul_f32_e32 v172, 0x3fb8aa3b, v172
	v_exp_f32_e32 v172, v172
	v_mul_f32_e32 v204, v9, v148
	v_mul_f32_e32 v204, 0x3fb8aa3b, v204
	v_exp_f32_e32 v204, v204
	s_nop 0
	v_mul_f32_e32 v184, v158, v184
	v_mul_f32_e32 v185, v159, v185
	v_mul_f32_e32 v186, v172, v186
	v_mul_f32_e32 v187, v204, v187
	v_add_u32_e32 v205, 0x10400, v11
	global_store_dwordx4 v205, v[184:187], s[0:1]
	v_add_u32_e32 v148, 66, v10
	v_cvt_f32_u32_e32 v148, v148
	v_fmamk_f32 v148, v148, 0x3d4541ff, v173
	v_mul_f32_e32 v158, v6, v148
	v_mul_f32_e32 v158, 0x3fb8aa3b, v158
	v_exp_f32_e32 v158, v158
	v_mul_f32_e32 v159, v7, v148
	v_mul_f32_e32 v159, 0x3fb8aa3b, v159
	v_exp_f32_e32 v159, v159
	v_mul_f32_e32 v172, v8, v148
	v_mul_f32_e32 v172, 0x3fb8aa3b, v172
	v_exp_f32_e32 v172, v172
	v_mul_f32_e32 v204, v9, v148
	v_mul_f32_e32 v204, 0x3fb8aa3b, v204
	v_exp_f32_e32 v204, v204
	s_nop 0
	v_mul_f32_e32 v188, v158, v188
	v_mul_f32_e32 v189, v159, v189
	v_mul_f32_e32 v190, v172, v190
	v_mul_f32_e32 v191, v204, v191
	v_add_u32_e32 v205, 0x10800, v11
	global_store_dwordx4 v205, v[188:191], s[0:1]
	v_add_u32_e32 v148, 67, v10
	v_cvt_f32_u32_e32 v148, v148
	v_fmamk_f32 v148, v148, 0x3d4541ff, v173
	v_mul_f32_e32 v158, v6, v148
	v_mul_f32_e32 v158, 0x3fb8aa3b, v158
	v_exp_f32_e32 v158, v158
	v_mul_f32_e32 v159, v7, v148
	v_mul_f32_e32 v159, 0x3fb8aa3b, v159
	v_exp_f32_e32 v159, v159
	v_mul_f32_e32 v172, v8, v148
	v_mul_f32_e32 v172, 0x3fb8aa3b, v172
	v_exp_f32_e32 v172, v172
	v_mul_f32_e32 v204, v9, v148
	v_mul_f32_e32 v204, 0x3fb8aa3b, v204
	v_exp_f32_e32 v204, v204
	s_nop 0
	v_mul_f32_e32 v192, v158, v192
	v_mul_f32_e32 v193, v159, v193
	v_mul_f32_e32 v194, v172, v194
	v_mul_f32_e32 v195, v204, v195
	v_add_u32_e32 v205, 0x10c00, v11
	global_store_dwordx4 v205, v[192:195], s[0:1]
	v_add_u32_e32 v148, 128, v10
	v_cvt_f32_u32_e32 v148, v148
	v_fmamk_f32 v148, v148, 0x3d4541ff, v173
	v_mul_f32_e32 v158, v6, v148
	v_mul_f32_e32 v158, 0x3fb8aa3b, v158
	v_exp_f32_e32 v158, v158
	v_mul_f32_e32 v159, v7, v148
	v_mul_f32_e32 v159, 0x3fb8aa3b, v159
	v_exp_f32_e32 v159, v159
	v_mul_f32_e32 v172, v8, v148
	v_mul_f32_e32 v172, 0x3fb8aa3b, v172
	v_exp_f32_e32 v172, v172
	v_mul_f32_e32 v204, v9, v148
	v_mul_f32_e32 v204, 0x3fb8aa3b, v204
	v_exp_f32_e32 v204, v204
	s_nop 0
	v_mul_f32_e32 v196, v158, v196
	v_mul_f32_e32 v197, v159, v197
	v_mul_f32_e32 v198, v172, v198
	v_mul_f32_e32 v199, v204, v199
	v_add_u32_e32 v205, 0x20000, v11
	global_store_dwordx4 v205, v[196:199], s[0:1]
	v_add_u32_e32 v148, 129, v10
	v_cvt_f32_u32_e32 v148, v148
	v_fmamk_f32 v148, v148, 0x3d4541ff, v173
	v_mul_f32_e32 v158, v6, v148
	v_mul_f32_e32 v158, 0x3fb8aa3b, v158
	v_exp_f32_e32 v158, v158
	v_mul_f32_e32 v159, v7, v148
	v_mul_f32_e32 v159, 0x3fb8aa3b, v159
	v_exp_f32_e32 v159, v159
	v_mul_f32_e32 v172, v8, v148
	v_mul_f32_e32 v172, 0x3fb8aa3b, v172
	v_exp_f32_e32 v172, v172
	v_mul_f32_e32 v204, v9, v148
	v_mul_f32_e32 v204, 0x3fb8aa3b, v204
	v_exp_f32_e32 v204, v204
	s_nop 0
	v_mul_f32_e32 v200, v158, v200
	v_mul_f32_e32 v201, v159, v201
	v_mul_f32_e32 v202, v172, v202
	v_mul_f32_e32 v203, v204, v203
	v_add_u32_e32 v205, 0x20400, v11
	global_store_dwordx4 v205, v[200:203], s[0:1]
	v_add_u32_e32 v148, 130, v10
	v_cvt_f32_u32_e32 v148, v148
	v_fmamk_f32 v148, v148, 0x3d4541ff, v173
	v_mul_f32_e32 v158, v6, v148
	v_mul_f32_e32 v158, 0x3fb8aa3b, v158
	v_exp_f32_e32 v158, v158
	v_mul_f32_e32 v159, v7, v148
	v_mul_f32_e32 v159, 0x3fb8aa3b, v159
	v_exp_f32_e32 v159, v159
	v_mul_f32_e32 v172, v8, v148
	v_mul_f32_e32 v172, 0x3fb8aa3b, v172
	v_exp_f32_e32 v172, v172
	v_mul_f32_e32 v204, v9, v148
	v_mul_f32_e32 v204, 0x3fb8aa3b, v204
	v_exp_f32_e32 v204, v204
	s_nop 0
	v_mul_f32_e32 v208, v158, v208
	v_mul_f32_e32 v209, v159, v209
	v_mul_f32_e32 v210, v172, v210
	v_mul_f32_e32 v211, v204, v211
	v_add_u32_e32 v205, 0x20800, v11
	global_store_dwordx4 v205, v[208:211], s[0:1]
	v_add_u32_e32 v148, 131, v10
	v_cvt_f32_u32_e32 v148, v148
	v_fmamk_f32 v148, v148, 0x3d4541ff, v173
	v_mul_f32_e32 v158, v6, v148
	v_mul_f32_e32 v158, 0x3fb8aa3b, v158
	v_exp_f32_e32 v158, v158
	v_mul_f32_e32 v159, v7, v148
	v_mul_f32_e32 v159, 0x3fb8aa3b, v159
	v_exp_f32_e32 v159, v159
	v_mul_f32_e32 v172, v8, v148
	v_mul_f32_e32 v172, 0x3fb8aa3b, v172
	v_exp_f32_e32 v172, v172
	v_mul_f32_e32 v204, v9, v148
	v_mul_f32_e32 v204, 0x3fb8aa3b, v204
	v_exp_f32_e32 v204, v204
	s_nop 0
	v_mul_f32_e32 v212, v158, v212
	v_mul_f32_e32 v213, v159, v213
	v_mul_f32_e32 v214, v172, v214
	v_mul_f32_e32 v215, v204, v215
	v_add_u32_e32 v205, 0x20c00, v11
	global_store_dwordx4 v205, v[212:215], s[0:1]
	v_add_u32_e32 v148, 192, v10
	v_cvt_f32_u32_e32 v148, v148
	v_fmamk_f32 v148, v148, 0x3d4541ff, v173
	v_mul_f32_e32 v158, v6, v148
	v_mul_f32_e32 v158, 0x3fb8aa3b, v158
	v_exp_f32_e32 v158, v158
	v_mul_f32_e32 v159, v7, v148
	v_mul_f32_e32 v159, 0x3fb8aa3b, v159
	v_exp_f32_e32 v159, v159
	v_mul_f32_e32 v172, v8, v148
	v_mul_f32_e32 v172, 0x3fb8aa3b, v172
	v_exp_f32_e32 v172, v172
	v_mul_f32_e32 v204, v9, v148
	v_mul_f32_e32 v204, 0x3fb8aa3b, v204
	v_exp_f32_e32 v204, v204
	s_nop 0
	v_mul_f32_e32 v216, v158, v216
	v_mul_f32_e32 v217, v159, v217
	v_mul_f32_e32 v218, v172, v218
	v_mul_f32_e32 v219, v204, v219
	v_add_u32_e32 v205, 0x30000, v11
	global_store_dwordx4 v205, v[216:219], s[0:1]
	v_add_u32_e32 v148, 193, v10
	v_cvt_f32_u32_e32 v148, v148
	v_fmamk_f32 v148, v148, 0x3d4541ff, v173
	v_mul_f32_e32 v158, v6, v148
	v_mul_f32_e32 v158, 0x3fb8aa3b, v158
	v_exp_f32_e32 v158, v158
	v_mul_f32_e32 v159, v7, v148
	v_mul_f32_e32 v159, 0x3fb8aa3b, v159
	v_exp_f32_e32 v159, v159
	v_mul_f32_e32 v172, v8, v148
	v_mul_f32_e32 v172, 0x3fb8aa3b, v172
	v_exp_f32_e32 v172, v172
	v_mul_f32_e32 v204, v9, v148
	v_mul_f32_e32 v204, 0x3fb8aa3b, v204
	v_exp_f32_e32 v204, v204
	s_nop 0
	v_mul_f32_e32 v220, v158, v220
	v_mul_f32_e32 v221, v159, v221
	v_mul_f32_e32 v222, v172, v222
	v_mul_f32_e32 v223, v204, v223
	v_add_u32_e32 v205, 0x30400, v11
	global_store_dwordx4 v205, v[220:223], s[0:1]
	v_add_u32_e32 v148, 194, v10
	v_cvt_f32_u32_e32 v148, v148
	v_fmamk_f32 v148, v148, 0x3d4541ff, v173
	v_mul_f32_e32 v158, v6, v148
	v_mul_f32_e32 v158, 0x3fb8aa3b, v158
	v_exp_f32_e32 v158, v158
	v_mul_f32_e32 v159, v7, v148
	v_mul_f32_e32 v159, 0x3fb8aa3b, v159
	v_exp_f32_e32 v159, v159
	v_mul_f32_e32 v172, v8, v148
	v_mul_f32_e32 v172, 0x3fb8aa3b, v172
	v_exp_f32_e32 v172, v172
	v_mul_f32_e32 v204, v9, v148
	v_mul_f32_e32 v204, 0x3fb8aa3b, v204
	v_exp_f32_e32 v204, v204
	s_nop 0
	v_mul_f32_e32 v224, v158, v224
	v_mul_f32_e32 v225, v159, v225
	v_mul_f32_e32 v226, v172, v226
	v_mul_f32_e32 v227, v204, v227
	v_add_u32_e32 v205, 0x30800, v11
	global_store_dwordx4 v205, v[224:227], s[0:1]
	v_add_u32_e32 v148, 195, v10
	v_cvt_f32_u32_e32 v148, v148
	v_fmamk_f32 v148, v148, 0x3d4541ff, v173
	v_mul_f32_e32 v158, v6, v148
	v_mul_f32_e32 v158, 0x3fb8aa3b, v158
	v_exp_f32_e32 v158, v158
	v_mul_f32_e32 v159, v7, v148
	v_mul_f32_e32 v159, 0x3fb8aa3b, v159
	v_exp_f32_e32 v159, v159
	v_mul_f32_e32 v172, v8, v148
	v_mul_f32_e32 v172, 0x3fb8aa3b, v172
	v_exp_f32_e32 v172, v172
	v_mul_f32_e32 v204, v9, v148
	v_mul_f32_e32 v204, 0x3fb8aa3b, v204
	v_exp_f32_e32 v204, v204
	s_nop 0
	v_mul_f32_e32 v228, v158, v228
	v_mul_f32_e32 v229, v159, v229
	v_mul_f32_e32 v230, v172, v230
	v_mul_f32_e32 v231, v204, v231
	v_add_u32_e32 v205, 0x30c00, v11
	global_store_dwordx4 v205, v[228:231], s[0:1]
	s_barrier
	s_mov_b64 s[0:1], 0

.LBB0_840:
	v_add_u32_e32 v9, s0, v7
	ds_read_b128 v[10:13], v8
	ds_read_b128 v[14:17], v8 offset:256
	ds_read_b128 v[18:21], v8 offset:512
	ds_read_b128 v[22:25], v8 offset:768
	ds_read_b128 v[26:29], v8 offset:1024
	ds_read_b128 v[30:33], v8 offset:1280
	ds_read_b128 v[34:37], v8 offset:1536
	ds_read_b128 v[38:41], v8 offset:1792
	ds_read_b128 v[42:45], v9
	ds_read_b128 v[48:51], v9 offset:16
	s_add_i32 s0, s0, 32
	v_add_u32_e32 v8, 0x800, v8
	s_cmpk_eq_i32 s0, 0x100
	s_waitcnt lgkmcnt(1)
	v_pk_fma_f32 v[2:3], v[42:43], v[10:11], v[2:3] op_sel_hi:[0,1,1]
	v_pk_fma_f32 v[4:5], v[42:43], v[12:13], v[4:5] op_sel_hi:[0,1,1]
	v_pk_fma_f32 v[2:3], v[42:43], v[14:15], v[2:3] op_sel:[1,0,0]
	v_pk_fma_f32 v[4:5], v[42:43], v[16:17], v[4:5] op_sel:[1,0,0]
	v_mov_b32_e32 v10, v45
	v_pk_fma_f32 v[2:3], v[44:45], v[18:19], v[2:3] op_sel_hi:[0,1,1]
	v_pk_fma_f32 v[4:5], v[44:45], v[20:21], v[4:5] op_sel_hi:[0,1,1]
	v_pk_fma_f32 v[2:3], v[10:11], v[22:23], v[2:3] op_sel_hi:[0,1,1]
	v_pk_fma_f32 v[4:5], v[10:11], v[24:25], v[4:5] op_sel_hi:[0,1,1]
	s_waitcnt lgkmcnt(0)
	v_pk_fma_f32 v[2:3], v[48:49], v[26:27], v[2:3] op_sel_hi:[0,1,1]
	v_pk_fma_f32 v[4:5], v[48:49], v[28:29], v[4:5] op_sel_hi:[0,1,1]
	v_pk_fma_f32 v[2:3], v[48:49], v[30:31], v[2:3] op_sel:[1,0,0]
	v_pk_fma_f32 v[4:5], v[48:49], v[32:33], v[4:5] op_sel:[1,0,0]
	v_mov_b32_e32 v12, v51
	v_pk_fma_f32 v[2:3], v[50:51], v[34:35], v[2:3] op_sel_hi:[0,1,1]
	v_pk_fma_f32 v[4:5], v[50:51], v[36:37], v[4:5] op_sel_hi:[0,1,1]
	v_pk_fma_f32 v[2:3], v[12:13], v[38:39], v[2:3] op_sel_hi:[0,1,1]
	v_pk_fma_f32 v[4:5], v[12:13], v[40:41], v[4:5] op_sel_hi:[0,1,1]
	s_cbranch_scc0 .LBB0_840
	ds_read_b128 v[8:11], v0 offset:29696
	s_lshl_b32 s0, s11, 23
	v_readlane_b32 s1, v250, 12
	s_add_u32 s4, s1, s0
	v_readlane_b32 s0, v250, 13
	s_waitcnt lgkmcnt(0)
	v_mul_f32_e32 v0, v2, v8
	v_mul_f32_e32 v2, 0.15915494, v0
	v_rndne_f32_e32 v2, v2
	v_fmac_f32_e32 v0, 0xc0c90fdb, v2
	v_fmac_f32_e32 v0, 0x343bbd2e, v2
	v_mul_f32_e32 v3, v3, v9
	v_mul_f32_e32 v0, 0.15915494, v0
	v_sin_f32_e32 v2, v0
	v_mul_f32_e32 v0, 0.15915494, v3
	v_rndne_f32_e32 v0, v0
	v_fmac_f32_e32 v3, 0xc0c90fdb, v0
	v_fmac_f32_e32 v3, 0x343bbd2e, v0
	v_mul_f32_e32 v0, 0.15915494, v3
	v_sin_f32_e32 v3, v0
	v_mul_f32_e32 v0, v4, v10
	v_mul_f32_e32 v4, 0.15915494, v0
	v_rndne_f32_e32 v4, v4
	v_fmac_f32_e32 v0, 0xc0c90fdb, v4
	v_fmac_f32_e32 v0, 0x343bbd2e, v4
	v_mul_f32_e32 v0, 0.15915494, v0
	v_sin_f32_e32 v4, v0
	v_mul_f32_e32 v0, v5, v11
	v_mul_f32_e32 v5, 0.15915494, v0
	v_rndne_f32_e32 v5, v5
	v_fmac_f32_e32 v0, 0xc0c90fdb, v5
	v_fmac_f32_e32 v0, 0x343bbd2e, v5
	v_mul_f32_e32 v0, 0.15915494, v0
	v_sin_f32_e32 v5, v0
	v_cvt_f32_ubyte0_e32 v0, v46
	s_addc_u32 s5, s0, 0
	s_lshl_b32 s0, s11, 18
	ds_write_b128 v6, v[2:5] offset:4096
	v_mov_b32_e32 v2, 0x40447cbd
	v_fmamk_f32 v0, v0, 0x3d4541ff, v2
	s_mov_b32 s100, s6
	v_cvt_f32_u32_e32 v2, s6
	s_mov_b32 s11, 0xc4ffe000
	s_add_u32 s0, s40, s0
	s_addc_u32 s1, s41, 0
	v_div_scale_f32 v4, s[8:9], s11, s11, v2
	v_rcp_f32_e32 v5, v4
	s_lshl_b32 s7, s6, 2
	s_add_u32 s4, s4, s7
	s_addc_u32 s5, s5, 0
	v_fma_f32 v8, -v4, v5, 1.0
	v_fmac_f32_e32 v5, v8, v5
	v_div_scale_f32 v8, vcc, v2, s11, v2
	s_or_b32 s7, s6, 1
	v_mul_f32_e32 v9, v8, v5
	v_cvt_f32_u32_e32 v3, s7
	v_fma_f32 v10, -v4, v9, v8
	v_fmac_f32_e32 v9, v10, v5
	v_fma_f32 v4, -v4, v9, v8
	v_div_fmas_f32 v4, v4, v5, v9
	v_div_fixup_f32 v2, v4, s11, v2
	v_div_scale_f32 v4, s[8:9], s11, s11, v3
	v_rcp_f32_e32 v5, v4
	v_mul_f32_e32 v2, v2, v0
	v_mul_f32_e32 v2, 0x3fb8aa3b, v2
	v_exp_f32_e32 v48, v2
	v_fma_f32 v2, -v4, v5, 1.0
	v_fmac_f32_e32 v5, v2, v5
	v_div_scale_f32 v2, vcc, v3, s11, v3
	s_or_b32 s7, s6, 2
	v_mul_f32_e32 v8, v2, v5
	v_cvt_f32_u32_e32 v6, s7
	v_fma_f32 v9, -v4, v8, v2
	v_fmac_f32_e32 v8, v9, v5
	v_fma_f32 v2, -v4, v8, v2
	v_div_fmas_f32 v2, v2, v5, v8
	v_div_fixup_f32 v2, v2, s11, v3
	v_div_scale_f32 v3, s[8:9], s11, s11, v6
	v_rcp_f32_e32 v4, v3
	v_mul_f32_e32 v2, v2, v0
	v_mul_f32_e32 v2, 0x3fb8aa3b, v2
	s_or_b32 s7, s6, 3
	v_exp_f32_e32 v49, v2
	v_fma_f32 v2, -v3, v4, 1.0
	v_cvt_f32_u32_e32 v7, s7
	v_fmac_f32_e32 v4, v2, v4
	v_div_scale_f32 v2, vcc, v6, s11, v6
	v_mul_f32_e32 v5, v2, v4
	v_fma_f32 v8, -v3, v5, v2
	v_fmac_f32_e32 v5, v8, v4
	v_fma_f32 v2, -v3, v5, v2
	v_div_scale_f32 v3, s[8:9], s11, s11, v7
	v_div_fmas_f32 v2, v2, v4, v5
	v_rcp_f32_e32 v4, v3
	v_div_fixup_f32 v2, v2, s11, v6
	v_mul_f32_e32 v2, v2, v0
	v_mul_f32_e32 v2, 0x3fb8aa3b, v2
	v_exp_f32_e32 v50, v2
	v_fma_f32 v2, -v3, v4, 1.0
	v_fmac_f32_e32 v4, v2, v4
	v_div_scale_f32 v2, vcc, v7, s11, v7
	v_mul_f32_e32 v5, v2, v4
	v_fma_f32 v6, -v3, v5, v2
	v_fmac_f32_e32 v5, v6, v4
	v_fma_f32 v2, -v3, v5, v2
	v_div_fmas_f32 v2, v2, v4, v5
	v_div_fixup_f32 v2, v2, s11, v7
	v_mul_f32_e32 v2, v2, v0
	v_mul_f32_e32 v2, 0x3fb8aa3b, v2
	s_or_b32 s7, s6, 4
	v_exp_f32_e32 v51, v2
	v_cvt_f32_u32_e32 v2, s7
	s_or_b32 s7, s6, 5
	v_cvt_f32_u32_e32 v3, s7
	s_or_b32 s7, s6, 6
	v_div_scale_f32 v4, s[8:9], s11, s11, v2
	v_rcp_f32_e32 v5, v4
	v_cvt_f32_u32_e32 v6, s7
	s_or_b32 s7, s6, 7
	v_cvt_f32_u32_e32 v7, s7
	v_fma_f32 v8, -v4, v5, 1.0
	v_fmac_f32_e32 v5, v8, v5
	v_div_scale_f32 v8, vcc, v2, s11, v2
	v_mul_f32_e32 v9, v8, v5
	v_fma_f32 v10, -v4, v9, v8
	v_fmac_f32_e32 v9, v10, v5
	v_fma_f32 v4, -v4, v9, v8
	v_div_fmas_f32 v4, v4, v5, v9
	v_div_fixup_f32 v2, v4, s11, v2
	v_div_scale_f32 v4, s[8:9], s11, s11, v3
	v_rcp_f32_e32 v5, v4
	v_mul_f32_e32 v2, v2, v0
	v_mul_f32_e32 v2, 0x3fb8aa3b, v2
	v_exp_f32_e32 v52, v2
	v_fma_f32 v2, -v4, v5, 1.0
	v_fmac_f32_e32 v5, v2, v5
	v_div_scale_f32 v2, vcc, v3, s11, v3
	v_mul_f32_e32 v8, v2, v5
	v_fma_f32 v9, -v4, v8, v2
	v_fmac_f32_e32 v8, v9, v5
	v_fma_f32 v2, -v4, v8, v2
	v_div_fmas_f32 v2, v2, v5, v8
	v_div_fixup_f32 v2, v2, s11, v3
	v_div_scale_f32 v3, s[8:9], s11, s11, v6
	v_rcp_f32_e32 v4, v3
	v_mul_f32_e32 v2, v2, v0
	v_mul_f32_e32 v2, 0x3fb8aa3b, v2
	v_exp_f32_e32 v53, v2
	v_fma_f32 v2, -v3, v4, 1.0
	v_fmac_f32_e32 v4, v2, v4
	v_div_scale_f32 v2, vcc, v6, s11, v6
	v_mul_f32_e32 v5, v2, v4
	v_fma_f32 v8, -v3, v5, v2
	v_fmac_f32_e32 v5, v8, v4
	v_fma_f32 v2, -v3, v5, v2
	v_div_scale_f32 v3, s[8:9], s11, s11, v7
	v_div_fmas_f32 v2, v2, v4, v5
	v_rcp_f32_e32 v4, v3
	v_div_fixup_f32 v2, v2, s11, v6
	v_mul_f32_e32 v2, v2, v0
	v_mul_f32_e32 v2, 0x3fb8aa3b, v2
	v_exp_f32_e32 v54, v2
	v_fma_f32 v2, -v3, v4, 1.0
	v_fmac_f32_e32 v4, v2, v4
	v_div_scale_f32 v2, vcc, v7, s11, v7
	v_mul_f32_e32 v5, v2, v4
	v_fma_f32 v6, -v3, v5, v2
	v_fmac_f32_e32 v5, v6, v4
	v_fma_f32 v2, -v3, v5, v2
	v_div_fmas_f32 v2, v2, v4, v5
	v_div_fixup_f32 v2, v2, s11, v7
	v_mul_f32_e32 v2, v2, v0
	v_mul_f32_e32 v2, 0x3fb8aa3b, v2
	s_or_b32 s7, s6, 8
	v_exp_f32_e32 v55, v2
	v_cvt_f32_u32_e32 v2, s7
	s_or_b32 s7, s6, 9
	v_cvt_f32_u32_e32 v3, s7
	s_or_b32 s7, s6, 10
	v_div_scale_f32 v4, s[8:9], s11, s11, v2
	v_rcp_f32_e32 v5, v4
	v_cvt_f32_u32_e32 v6, s7
	s_or_b32 s7, s6, 11
	v_cvt_f32_u32_e32 v7, s7
	v_fma_f32 v8, -v4, v5, 1.0
	v_fmac_f32_e32 v5, v8, v5
	v_div_scale_f32 v8, vcc, v2, s11, v2
	v_mul_f32_e32 v9, v8, v5
	v_fma_f32 v10, -v4, v9, v8
	v_fmac_f32_e32 v9, v10, v5
	v_fma_f32 v4, -v4, v9, v8
	v_div_fmas_f32 v4, v4, v5, v9
	v_div_fixup_f32 v2, v4, s11, v2
	v_div_scale_f32 v4, s[8:9], s11, s11, v3
	v_rcp_f32_e32 v5, v4
	v_mul_f32_e32 v2, v2, v0
	v_mul_f32_e32 v2, 0x3fb8aa3b, v2
	v_exp_f32_e32 v56, v2
	v_fma_f32 v2, -v4, v5, 1.0
	v_fmac_f32_e32 v5, v2, v5
	v_div_scale_f32 v2, vcc, v3, s11, v3
	v_mul_f32_e32 v8, v2, v5
	v_fma_f32 v9, -v4, v8, v2
	v_fmac_f32_e32 v8, v9, v5
	v_fma_f32 v2, -v4, v8, v2
	v_div_fmas_f32 v2, v2, v5, v8
	v_div_fixup_f32 v2, v2, s11, v3
	v_div_scale_f32 v3, s[8:9], s11, s11, v6
	v_rcp_f32_e32 v4, v3
	v_mul_f32_e32 v2, v2, v0
	v_mul_f32_e32 v2, 0x3fb8aa3b, v2
	v_exp_f32_e32 v57, v2
	v_fma_f32 v2, -v3, v4, 1.0
	v_fmac_f32_e32 v4, v2, v4
	v_div_scale_f32 v2, vcc, v6, s11, v6
	v_mul_f32_e32 v5, v2, v4
	v_fma_f32 v8, -v3, v5, v2
	v_fmac_f32_e32 v5, v8, v4
	v_fma_f32 v2, -v3, v5, v2
	v_div_scale_f32 v3, s[8:9], s11, s11, v7
	v_div_fmas_f32 v2, v2, v4, v5
	v_rcp_f32_e32 v4, v3
	v_div_fixup_f32 v2, v2, s11, v6
	v_mul_f32_e32 v2, v2, v0
	v_mul_f32_e32 v2, 0x3fb8aa3b, v2
	v_exp_f32_e32 v58, v2
	v_fma_f32 v2, -v3, v4, 1.0
	v_fmac_f32_e32 v4, v2, v4
	v_div_scale_f32 v2, vcc, v7, s11, v7
	v_mul_f32_e32 v5, v2, v4
	v_fma_f32 v6, -v3, v5, v2
	v_fmac_f32_e32 v5, v6, v4
	v_fma_f32 v2, -v3, v5, v2
	v_div_fmas_f32 v2, v2, v4, v5
	v_div_fixup_f32 v2, v2, s11, v7
	v_mul_f32_e32 v2, v2, v0
	v_mul_f32_e32 v2, 0x3fb8aa3b, v2
	s_or_b32 s7, s6, 12
	v_exp_f32_e32 v59, v2
	v_cvt_f32_u32_e32 v2, s7
	s_or_b32 s7, s6, 13
	v_cvt_f32_u32_e32 v3, s7
	s_or_b32 s7, s6, 14
	v_div_scale_f32 v4, s[8:9], s11, s11, v2
	v_rcp_f32_e32 v5, v4
	s_or_b32 s6, s6, 15
	v_cvt_f32_u32_e32 v6, s7
	v_cvt_f32_u32_e32 v7, s6
	v_fma_f32 v8, -v4, v5, 1.0
	v_fmac_f32_e32 v5, v8, v5
	v_div_scale_f32 v8, vcc, v2, s11, v2
	v_mul_f32_e32 v9, v8, v5
	v_fma_f32 v10, -v4, v9, v8
	v_fmac_f32_e32 v9, v10, v5
	v_fma_f32 v4, -v4, v9, v8
	v_div_fmas_f32 v4, v4, v5, v9
	v_div_fixup_f32 v2, v4, s11, v2
	v_div_scale_f32 v4, s[6:7], s11, s11, v3
	v_rcp_f32_e32 v5, v4
	v_mul_f32_e32 v2, v2, v0
	v_mul_f32_e32 v2, 0x3fb8aa3b, v2
	v_exp_f32_e32 v60, v2
	v_fma_f32 v2, -v4, v5, 1.0
	v_fmac_f32_e32 v5, v2, v5
	v_div_scale_f32 v2, vcc, v3, s11, v3
	v_mul_f32_e32 v8, v2, v5
	v_fma_f32 v9, -v4, v8, v2
	v_fmac_f32_e32 v8, v9, v5
	v_fma_f32 v2, -v4, v8, v2
	v_div_fmas_f32 v2, v2, v5, v8
	v_div_fixup_f32 v2, v2, s11, v3
	v_div_scale_f32 v3, s[6:7], s11, s11, v6
	v_rcp_f32_e32 v4, v3
	v_mul_f32_e32 v2, v2, v0
	v_mul_f32_e32 v2, 0x3fb8aa3b, v2
	v_exp_f32_e32 v61, v2
	v_fma_f32 v2, -v3, v4, 1.0
	v_fmac_f32_e32 v4, v2, v4
	v_div_scale_f32 v2, vcc, v6, s11, v6
	v_mul_f32_e32 v5, v2, v4
	v_fma_f32 v8, -v3, v5, v2
	v_fmac_f32_e32 v5, v8, v4
	v_fma_f32 v2, -v3, v5, v2
	v_div_scale_f32 v3, s[6:7], s11, s11, v7
	v_div_fmas_f32 v2, v2, v4, v5
	v_rcp_f32_e32 v4, v3
	v_div_fixup_f32 v2, v2, s11, v6
	v_mul_f32_e32 v2, v2, v0
	v_mul_f32_e32 v2, 0x3fb8aa3b, v2
	v_exp_f32_e32 v62, v2
	v_fma_f32 v2, -v3, v4, 1.0
	v_fmac_f32_e32 v4, v2, v4
	v_div_scale_f32 v2, vcc, v7, s11, v7
	v_mul_f32_e32 v5, v2, v4
	v_fma_f32 v6, -v3, v5, v2
	v_fmac_f32_e32 v5, v6, v4
	v_fma_f32 v2, -v3, v5, v2
	v_div_fmas_f32 v2, v2, v4, v5
	v_div_fixup_f32 v2, v2, s11, v7
	v_mul_f32_e32 v0, v2, v0
	v_mul_f32_e32 v0, 0x3fb8aa3b, v0
	v_exp_f32_e32 v63, v0
	s_mov_b32 s8, 0
	s_waitcnt lgkmcnt(0)
	s_barrier
.LBB0_842:
	v_mov_b32_e32 v13, s100
	v_and_b32_e32 v2, 15, v207
	v_lshrrev_b32_e32 v3, 4, v207
	v_lshrrev_b32_e32 v205, 6, v175
	v_lshlrev_b32_e32 v4, 8, v2
	v_lshl_add_u32 v4, v3, 2, v4
	ds_read_b32 v14, v4 offset:4096
	ds_read_b32 v15, v4 offset:4112
	ds_read_b32 v16, v4 offset:4128
	ds_read_b32 v17, v4 offset:4144
	ds_read_b32 v18, v4 offset:4160
	ds_read_b32 v19, v4 offset:4176
	ds_read_b32 v20, v4 offset:4192
	ds_read_b32 v21, v4 offset:4208
	ds_read_b32 v22, v4 offset:4224
	ds_read_b32 v23, v4 offset:4240
	ds_read_b32 v24, v4 offset:4256
	ds_read_b32 v25, v4 offset:4272
	ds_read_b32 v26, v4 offset:4288
	ds_read_b32 v27, v4 offset:4304
	ds_read_b32 v28, v4 offset:4320
	ds_read_b32 v29, v4 offset:4336
	v_lshlrev_b32_e32 v5, 12, v3
	v_lshl_add_u32 v5, v2, 4, v5
	v_lshl_add_u32 v5, v205, 10, v5
	s_mov_b32 s8, s0
	s_mov_b32 s9, s1
	v_mov_b32_e32 v160, 0
	v_mov_b32_e32 v161, 0
	v_mov_b32_e32 v162, 0
	v_mov_b32_e32 v163, 0
	v_mov_b32_e32 v164, 0
	v_mov_b32_e32 v165, 0
	v_mov_b32_e32 v166, 0
	v_mov_b32_e32 v167, 0
	v_mov_b32_e32 v168, 0
	v_mov_b32_e32 v169, 0
	v_mov_b32_e32 v170, 0
	v_mov_b32_e32 v171, 0
	v_mov_b32_e32 v176, 0
	v_mov_b32_e32 v177, 0
	v_mov_b32_e32 v178, 0
	v_mov_b32_e32 v179, 0
	v_mov_b32_e32 v180, 0
	v_mov_b32_e32 v181, 0
	v_mov_b32_e32 v182, 0
	v_mov_b32_e32 v183, 0
	v_mov_b32_e32 v184, 0
	v_mov_b32_e32 v185, 0
	v_mov_b32_e32 v186, 0
	v_mov_b32_e32 v187, 0
	v_mov_b32_e32 v188, 0
	v_mov_b32_e32 v189, 0
	v_mov_b32_e32 v190, 0
	v_mov_b32_e32 v191, 0
	v_mov_b32_e32 v192, 0
	v_mov_b32_e32 v193, 0
	v_mov_b32_e32 v194, 0
	v_mov_b32_e32 v195, 0
	v_mov_b32_e32 v196, 0
	v_mov_b32_e32 v197, 0
	v_mov_b32_e32 v198, 0
	v_mov_b32_e32 v199, 0
	v_mov_b32_e32 v200, 0
	v_mov_b32_e32 v201, 0
	v_mov_b32_e32 v202, 0
	v_mov_b32_e32 v203, 0
	v_mov_b32_e32 v208, 0
	v_mov_b32_e32 v209, 0
	v_mov_b32_e32 v210, 0
	v_mov_b32_e32 v211, 0
	v_mov_b32_e32 v212, 0
	v_mov_b32_e32 v213, 0
	v_mov_b32_e32 v214, 0
	v_mov_b32_e32 v215, 0
	v_mov_b32_e32 v216, 0
	v_mov_b32_e32 v217, 0
	v_mov_b32_e32 v218, 0
	v_mov_b32_e32 v219, 0
	v_mov_b32_e32 v220, 0
	v_mov_b32_e32 v221, 0
	v_mov_b32_e32 v222, 0
	v_mov_b32_e32 v223, 0
	v_mov_b32_e32 v224, 0
	v_mov_b32_e32 v225, 0
	v_mov_b32_e32 v226, 0
	v_mov_b32_e32 v227, 0
	v_mov_b32_e32 v228, 0
	v_mov_b32_e32 v229, 0
	v_mov_b32_e32 v230, 0
	v_mov_b32_e32 v231, 0
	global_load_dwordx4 v[30:33], v5, s[8:9]
	global_load_dwordx4 v[34:37], v5, s[8:9] offset:256
	global_load_dwordx4 v[38:41], v5, s[8:9] offset:512
	global_load_dwordx4 v[42:45], v5, s[8:9] offset:768
	s_add_u32 s8, s8, 0x4000
	s_addc_u32 s9, s9, 0
	s_waitcnt lgkmcnt(0)
	global_load_dwordx4 v[132:135], v5, s[8:9]
	global_load_dwordx4 v[136:139], v5, s[8:9] offset:256
	global_load_dwordx4 v[140:143], v5, s[8:9] offset:512
	global_load_dwordx4 v[144:147], v5, s[8:9] offset:768
	s_add_u32 s8, s8, 0x4000
	s_addc_u32 s9, s9, 0
	s_waitcnt vmcnt(4)
	v_mfma_f32_16x16x4_f32 v[160:163], v14, v30, v[160:163]
	v_mfma_f32_16x16x4_f32 v[164:167], v14, v31, v[164:167]
	v_mfma_f32_16x16x4_f32 v[168:171], v14, v32, v[168:171]
	v_mfma_f32_16x16x4_f32 v[176:179], v14, v33, v[176:179]
	v_mfma_f32_16x16x4_f32 v[180:183], v14, v34, v[180:183]
	v_mfma_f32_16x16x4_f32 v[184:187], v14, v35, v[184:187]
	v_mfma_f32_16x16x4_f32 v[188:191], v14, v36, v[188:191]
	v_mfma_f32_16x16x4_f32 v[192:195], v14, v37, v[192:195]
	v_mfma_f32_16x16x4_f32 v[196:199], v14, v38, v[196:199]
	v_mfma_f32_16x16x4_f32 v[200:203], v14, v39, v[200:203]
	v_mfma_f32_16x16x4_f32 v[208:211], v14, v40, v[208:211]
	v_mfma_f32_16x16x4_f32 v[212:215], v14, v41, v[212:215]
	v_mfma_f32_16x16x4_f32 v[216:219], v14, v42, v[216:219]
	v_mfma_f32_16x16x4_f32 v[220:223], v14, v43, v[220:223]
	v_mfma_f32_16x16x4_f32 v[224:227], v14, v44, v[224:227]
	v_mfma_f32_16x16x4_f32 v[228:231], v14, v45, v[228:231]
	global_load_dwordx4 v[30:33], v5, s[8:9]
	global_load_dwordx4 v[34:37], v5, s[8:9] offset:256
	global_load_dwordx4 v[38:41], v5, s[8:9] offset:512
	global_load_dwordx4 v[42:45], v5, s[8:9] offset:768
	s_add_u32 s8, s8, 0x4000
	s_addc_u32 s9, s9, 0
	s_waitcnt vmcnt(4)
	v_mfma_f32_16x16x4_f32 v[160:163], v15, v132, v[160:163]
	v_mfma_f32_16x16x4_f32 v[164:167], v15, v133, v[164:167]
	v_mfma_f32_16x16x4_f32 v[168:171], v15, v134, v[168:171]
	v_mfma_f32_16x16x4_f32 v[176:179], v15, v135, v[176:179]
	v_mfma_f32_16x16x4_f32 v[180:183], v15, v136, v[180:183]
	v_mfma_f32_16x16x4_f32 v[184:187], v15, v137, v[184:187]
	v_mfma_f32_16x16x4_f32 v[188:191], v15, v138, v[188:191]
	v_mfma_f32_16x16x4_f32 v[192:195], v15, v139, v[192:195]
	v_mfma_f32_16x16x4_f32 v[196:199], v15, v140, v[196:199]
	v_mfma_f32_16x16x4_f32 v[200:203], v15, v141, v[200:203]
	v_mfma_f32_16x16x4_f32 v[208:211], v15, v142, v[208:211]
	v_mfma_f32_16x16x4_f32 v[212:215], v15, v143, v[212:215]
	v_mfma_f32_16x16x4_f32 v[216:219], v15, v144, v[216:219]
	v_mfma_f32_16x16x4_f32 v[220:223], v15, v145, v[220:223]
	v_mfma_f32_16x16x4_f32 v[224:227], v15, v146, v[224:227]
	v_mfma_f32_16x16x4_f32 v[228:231], v15, v147, v[228:231]
	global_load_dwordx4 v[132:135], v5, s[8:9]
	global_load_dwordx4 v[136:139], v5, s[8:9] offset:256
	global_load_dwordx4 v[140:143], v5, s[8:9] offset:512
	global_load_dwordx4 v[144:147], v5, s[8:9] offset:768
	s_add_u32 s8, s8, 0x4000
	s_addc_u32 s9, s9, 0
	s_waitcnt vmcnt(4)
	v_mfma_f32_16x16x4_f32 v[160:163], v16, v30, v[160:163]
	v_mfma_f32_16x16x4_f32 v[164:167], v16, v31, v[164:167]
	v_mfma_f32_16x16x4_f32 v[168:171], v16, v32, v[168:171]
	v_mfma_f32_16x16x4_f32 v[176:179], v16, v33, v[176:179]
	v_mfma_f32_16x16x4_f32 v[180:183], v16, v34, v[180:183]
	v_mfma_f32_16x16x4_f32 v[184:187], v16, v35, v[184:187]
	v_mfma_f32_16x16x4_f32 v[188:191], v16, v36, v[188:191]
	v_mfma_f32_16x16x4_f32 v[192:195], v16, v37, v[192:195]
	v_mfma_f32_16x16x4_f32 v[196:199], v16, v38, v[196:199]
	v_mfma_f32_16x16x4_f32 v[200:203], v16, v39, v[200:203]
	v_mfma_f32_16x16x4_f32 v[208:211], v16, v40, v[208:211]
	v_mfma_f32_16x16x4_f32 v[212:215], v16, v41, v[212:215]
	v_mfma_f32_16x16x4_f32 v[216:219], v16, v42, v[216:219]
	v_mfma_f32_16x16x4_f32 v[220:223], v16, v43, v[220:223]
	v_mfma_f32_16x16x4_f32 v[224:227], v16, v44, v[224:227]
	v_mfma_f32_16x16x4_f32 v[228:231], v16, v45, v[228:231]
	global_load_dwordx4 v[30:33], v5, s[8:9]
	global_load_dwordx4 v[34:37], v5, s[8:9] offset:256
	global_load_dwordx4 v[38:41], v5, s[8:9] offset:512
	global_load_dwordx4 v[42:45], v5, s[8:9] offset:768
	s_add_u32 s8, s8, 0x4000
	s_addc_u32 s9, s9, 0
	s_waitcnt vmcnt(4)
	v_mfma_f32_16x16x4_f32 v[160:163], v17, v132, v[160:163]
	v_mfma_f32_16x16x4_f32 v[164:167], v17, v133, v[164:167]
	v_mfma_f32_16x16x4_f32 v[168:171], v17, v134, v[168:171]
	v_mfma_f32_16x16x4_f32 v[176:179], v17, v135, v[176:179]
	v_mfma_f32_16x16x4_f32 v[180:183], v17, v136, v[180:183]
	v_mfma_f32_16x16x4_f32 v[184:187], v17, v137, v[184:187]
	v_mfma_f32_16x16x4_f32 v[188:191], v17, v138, v[188:191]
	v_mfma_f32_16x16x4_f32 v[192:195], v17, v139, v[192:195]
	v_mfma_f32_16x16x4_f32 v[196:199], v17, v140, v[196:199]
	v_mfma_f32_16x16x4_f32 v[200:203], v17, v141, v[200:203]
	v_mfma_f32_16x16x4_f32 v[208:211], v17, v142, v[208:211]
	v_mfma_f32_16x16x4_f32 v[212:215], v17, v143, v[212:215]
	v_mfma_f32_16x16x4_f32 v[216:219], v17, v144, v[216:219]
	v_mfma_f32_16x16x4_f32 v[220:223], v17, v145, v[220:223]
	v_mfma_f32_16x16x4_f32 v[224:227], v17, v146, v[224:227]
	v_mfma_f32_16x16x4_f32 v[228:231], v17, v147, v[228:231]
	global_load_dwordx4 v[132:135], v5, s[8:9]
	global_load_dwordx4 v[136:139], v5, s[8:9] offset:256
	global_load_dwordx4 v[140:143], v5, s[8:9] offset:512
	global_load_dwordx4 v[144:147], v5, s[8:9] offset:768
	s_add_u32 s8, s8, 0x4000
	s_addc_u32 s9, s9, 0
	s_waitcnt vmcnt(4)
	v_mfma_f32_16x16x4_f32 v[160:163], v18, v30, v[160:163]
	v_mfma_f32_16x16x4_f32 v[164:167], v18, v31, v[164:167]
	v_mfma_f32_16x16x4_f32 v[168:171], v18, v32, v[168:171]
	v_mfma_f32_16x16x4_f32 v[176:179], v18, v33, v[176:179]
	v_mfma_f32_16x16x4_f32 v[180:183], v18, v34, v[180:183]
	v_mfma_f32_16x16x4_f32 v[184:187], v18, v35, v[184:187]
	v_mfma_f32_16x16x4_f32 v[188:191], v18, v36, v[188:191]
	v_mfma_f32_16x16x4_f32 v[192:195], v18, v37, v[192:195]
	v_mfma_f32_16x16x4_f32 v[196:199], v18, v38, v[196:199]
	v_mfma_f32_16x16x4_f32 v[200:203], v18, v39, v[200:203]
	v_mfma_f32_16x16x4_f32 v[208:211], v18, v40, v[208:211]
	v_mfma_f32_16x16x4_f32 v[212:215], v18, v41, v[212:215]
	v_mfma_f32_16x16x4_f32 v[216:219], v18, v42, v[216:219]
	v_mfma_f32_16x16x4_f32 v[220:223], v18, v43, v[220:223]
	v_mfma_f32_16x16x4_f32 v[224:227], v18, v44, v[224:227]
	v_mfma_f32_16x16x4_f32 v[228:231], v18, v45, v[228:231]
	global_load_dwordx4 v[30:33], v5, s[8:9]
	global_load_dwordx4 v[34:37], v5, s[8:9] offset:256
	global_load_dwordx4 v[38:41], v5, s[8:9] offset:512
	global_load_dwordx4 v[42:45], v5, s[8:9] offset:768
	s_add_u32 s8, s8, 0x4000
	s_addc_u32 s9, s9, 0
	s_waitcnt vmcnt(4)
	v_mfma_f32_16x16x4_f32 v[160:163], v19, v132, v[160:163]
	v_mfma_f32_16x16x4_f32 v[164:167], v19, v133, v[164:167]
	v_mfma_f32_16x16x4_f32 v[168:171], v19, v134, v[168:171]
	v_mfma_f32_16x16x4_f32 v[176:179], v19, v135, v[176:179]
	v_mfma_f32_16x16x4_f32 v[180:183], v19, v136, v[180:183]
	v_mfma_f32_16x16x4_f32 v[184:187], v19, v137, v[184:187]
	v_mfma_f32_16x16x4_f32 v[188:191], v19, v138, v[188:191]
	v_mfma_f32_16x16x4_f32 v[192:195], v19, v139, v[192:195]
	v_mfma_f32_16x16x4_f32 v[196:199], v19, v140, v[196:199]
	v_mfma_f32_16x16x4_f32 v[200:203], v19, v141, v[200:203]
	v_mfma_f32_16x16x4_f32 v[208:211], v19, v142, v[208:211]
	v_mfma_f32_16x16x4_f32 v[212:215], v19, v143, v[212:215]
	v_mfma_f32_16x16x4_f32 v[216:219], v19, v144, v[216:219]
	v_mfma_f32_16x16x4_f32 v[220:223], v19, v145, v[220:223]
	v_mfma_f32_16x16x4_f32 v[224:227], v19, v146, v[224:227]
	v_mfma_f32_16x16x4_f32 v[228:231], v19, v147, v[228:231]
	global_load_dwordx4 v[132:135], v5, s[8:9]
	global_load_dwordx4 v[136:139], v5, s[8:9] offset:256
	global_load_dwordx4 v[140:143], v5, s[8:9] offset:512
	global_load_dwordx4 v[144:147], v5, s[8:9] offset:768
	s_add_u32 s8, s8, 0x4000
	s_addc_u32 s9, s9, 0
	s_waitcnt vmcnt(4)
	v_mfma_f32_16x16x4_f32 v[160:163], v20, v30, v[160:163]
	v_mfma_f32_16x16x4_f32 v[164:167], v20, v31, v[164:167]
	v_mfma_f32_16x16x4_f32 v[168:171], v20, v32, v[168:171]
	v_mfma_f32_16x16x4_f32 v[176:179], v20, v33, v[176:179]
	v_mfma_f32_16x16x4_f32 v[180:183], v20, v34, v[180:183]
	v_mfma_f32_16x16x4_f32 v[184:187], v20, v35, v[184:187]
	v_mfma_f32_16x16x4_f32 v[188:191], v20, v36, v[188:191]
	v_mfma_f32_16x16x4_f32 v[192:195], v20, v37, v[192:195]
	v_mfma_f32_16x16x4_f32 v[196:199], v20, v38, v[196:199]
	v_mfma_f32_16x16x4_f32 v[200:203], v20, v39, v[200:203]
	v_mfma_f32_16x16x4_f32 v[208:211], v20, v40, v[208:211]
	v_mfma_f32_16x16x4_f32 v[212:215], v20, v41, v[212:215]
	v_mfma_f32_16x16x4_f32 v[216:219], v20, v42, v[216:219]
	v_mfma_f32_16x16x4_f32 v[220:223], v20, v43, v[220:223]
	v_mfma_f32_16x16x4_f32 v[224:227], v20, v44, v[224:227]
	v_mfma_f32_16x16x4_f32 v[228:231], v20, v45, v[228:231]
	global_load_dwordx4 v[30:33], v5, s[8:9]
	global_load_dwordx4 v[34:37], v5, s[8:9] offset:256
	global_load_dwordx4 v[38:41], v5, s[8:9] offset:512
	global_load_dwordx4 v[42:45], v5, s[8:9] offset:768
	s_add_u32 s8, s8, 0x4000
	s_addc_u32 s9, s9, 0
	s_waitcnt vmcnt(4)
	v_mfma_f32_16x16x4_f32 v[160:163], v21, v132, v[160:163]
	v_mfma_f32_16x16x4_f32 v[164:167], v21, v133, v[164:167]
	v_mfma_f32_16x16x4_f32 v[168:171], v21, v134, v[168:171]
	v_mfma_f32_16x16x4_f32 v[176:179], v21, v135, v[176:179]
	v_mfma_f32_16x16x4_f32 v[180:183], v21, v136, v[180:183]
	v_mfma_f32_16x16x4_f32 v[184:187], v21, v137, v[184:187]
	v_mfma_f32_16x16x4_f32 v[188:191], v21, v138, v[188:191]
	v_mfma_f32_16x16x4_f32 v[192:195], v21, v139, v[192:195]
	v_mfma_f32_16x16x4_f32 v[196:199], v21, v140, v[196:199]
	v_mfma_f32_16x16x4_f32 v[200:203], v21, v141, v[200:203]
	v_mfma_f32_16x16x4_f32 v[208:211], v21, v142, v[208:211]
	v_mfma_f32_16x16x4_f32 v[212:215], v21, v143, v[212:215]
	v_mfma_f32_16x16x4_f32 v[216:219], v21, v144, v[216:219]
	v_mfma_f32_16x16x4_f32 v[220:223], v21, v145, v[220:223]
	v_mfma_f32_16x16x4_f32 v[224:227], v21, v146, v[224:227]
	v_mfma_f32_16x16x4_f32 v[228:231], v21, v147, v[228:231]
	global_load_dwordx4 v[132:135], v5, s[8:9]
	global_load_dwordx4 v[136:139], v5, s[8:9] offset:256
	global_load_dwordx4 v[140:143], v5, s[8:9] offset:512
	global_load_dwordx4 v[144:147], v5, s[8:9] offset:768
	s_add_u32 s8, s8, 0x4000
	s_addc_u32 s9, s9, 0
	s_waitcnt vmcnt(4)
	v_mfma_f32_16x16x4_f32 v[160:163], v22, v30, v[160:163]
	v_mfma_f32_16x16x4_f32 v[164:167], v22, v31, v[164:167]
	v_mfma_f32_16x16x4_f32 v[168:171], v22, v32, v[168:171]
	v_mfma_f32_16x16x4_f32 v[176:179], v22, v33, v[176:179]
	v_mfma_f32_16x16x4_f32 v[180:183], v22, v34, v[180:183]
	v_mfma_f32_16x16x4_f32 v[184:187], v22, v35, v[184:187]
	v_mfma_f32_16x16x4_f32 v[188:191], v22, v36, v[188:191]
	v_mfma_f32_16x16x4_f32 v[192:195], v22, v37, v[192:195]
	v_mfma_f32_16x16x4_f32 v[196:199], v22, v38, v[196:199]
	v_mfma_f32_16x16x4_f32 v[200:203], v22, v39, v[200:203]
	v_mfma_f32_16x16x4_f32 v[208:211], v22, v40, v[208:211]
	v_mfma_f32_16x16x4_f32 v[212:215], v22, v41, v[212:215]
	v_mfma_f32_16x16x4_f32 v[216:219], v22, v42, v[216:219]
	v_mfma_f32_16x16x4_f32 v[220:223], v22, v43, v[220:223]
	v_mfma_f32_16x16x4_f32 v[224:227], v22, v44, v[224:227]
	v_mfma_f32_16x16x4_f32 v[228:231], v22, v45, v[228:231]
	global_load_dwordx4 v[30:33], v5, s[8:9]
	global_load_dwordx4 v[34:37], v5, s[8:9] offset:256
	global_load_dwordx4 v[38:41], v5, s[8:9] offset:512
	global_load_dwordx4 v[42:45], v5, s[8:9] offset:768
	s_add_u32 s8, s8, 0x4000
	s_addc_u32 s9, s9, 0
	s_waitcnt vmcnt(4)
	v_mfma_f32_16x16x4_f32 v[160:163], v23, v132, v[160:163]
	v_mfma_f32_16x16x4_f32 v[164:167], v23, v133, v[164:167]
	v_mfma_f32_16x16x4_f32 v[168:171], v23, v134, v[168:171]
	v_mfma_f32_16x16x4_f32 v[176:179], v23, v135, v[176:179]
	v_mfma_f32_16x16x4_f32 v[180:183], v23, v136, v[180:183]
	v_mfma_f32_16x16x4_f32 v[184:187], v23, v137, v[184:187]
	v_mfma_f32_16x16x4_f32 v[188:191], v23, v138, v[188:191]
	v_mfma_f32_16x16x4_f32 v[192:195], v23, v139, v[192:195]
	v_mfma_f32_16x16x4_f32 v[196:199], v23, v140, v[196:199]
	v_mfma_f32_16x16x4_f32 v[200:203], v23, v141, v[200:203]
	v_mfma_f32_16x16x4_f32 v[208:211], v23, v142, v[208:211]
	v_mfma_f32_16x16x4_f32 v[212:215], v23, v143, v[212:215]
	v_mfma_f32_16x16x4_f32 v[216:219], v23, v144, v[216:219]
	v_mfma_f32_16x16x4_f32 v[220:223], v23, v145, v[220:223]
	v_mfma_f32_16x16x4_f32 v[224:227], v23, v146, v[224:227]
	v_mfma_f32_16x16x4_f32 v[228:231], v23, v147, v[228:231]
	global_load_dwordx4 v[132:135], v5, s[8:9]
	global_load_dwordx4 v[136:139], v5, s[8:9] offset:256
	global_load_dwordx4 v[140:143], v5, s[8:9] offset:512
	global_load_dwordx4 v[144:147], v5, s[8:9] offset:768
	s_add_u32 s8, s8, 0x4000
	s_addc_u32 s9, s9, 0
	s_waitcnt vmcnt(4)
	v_mfma_f32_16x16x4_f32 v[160:163], v24, v30, v[160:163]
	v_mfma_f32_16x16x4_f32 v[164:167], v24, v31, v[164:167]
	v_mfma_f32_16x16x4_f32 v[168:171], v24, v32, v[168:171]
	v_mfma_f32_16x16x4_f32 v[176:179], v24, v33, v[176:179]
	v_mfma_f32_16x16x4_f32 v[180:183], v24, v34, v[180:183]
	v_mfma_f32_16x16x4_f32 v[184:187], v24, v35, v[184:187]
	v_mfma_f32_16x16x4_f32 v[188:191], v24, v36, v[188:191]
	v_mfma_f32_16x16x4_f32 v[192:195], v24, v37, v[192:195]
	v_mfma_f32_16x16x4_f32 v[196:199], v24, v38, v[196:199]
	v_mfma_f32_16x16x4_f32 v[200:203], v24, v39, v[200:203]
	v_mfma_f32_16x16x4_f32 v[208:211], v24, v40, v[208:211]
	v_mfma_f32_16x16x4_f32 v[212:215], v24, v41, v[212:215]
	v_mfma_f32_16x16x4_f32 v[216:219], v24, v42, v[216:219]
	v_mfma_f32_16x16x4_f32 v[220:223], v24, v43, v[220:223]
	v_mfma_f32_16x16x4_f32 v[224:227], v24, v44, v[224:227]
	v_mfma_f32_16x16x4_f32 v[228:231], v24, v45, v[228:231]
	global_load_dwordx4 v[30:33], v5, s[8:9]
	global_load_dwordx4 v[34:37], v5, s[8:9] offset:256
	global_load_dwordx4 v[38:41], v5, s[8:9] offset:512
	global_load_dwordx4 v[42:45], v5, s[8:9] offset:768
	s_add_u32 s8, s8, 0x4000
	s_addc_u32 s9, s9, 0
	s_waitcnt vmcnt(4)
	v_mfma_f32_16x16x4_f32 v[160:163], v25, v132, v[160:163]
	v_mfma_f32_16x16x4_f32 v[164:167], v25, v133, v[164:167]
	v_mfma_f32_16x16x4_f32 v[168:171], v25, v134, v[168:171]
	v_mfma_f32_16x16x4_f32 v[176:179], v25, v135, v[176:179]
	v_mfma_f32_16x16x4_f32 v[180:183], v25, v136, v[180:183]
	v_mfma_f32_16x16x4_f32 v[184:187], v25, v137, v[184:187]
	v_mfma_f32_16x16x4_f32 v[188:191], v25, v138, v[188:191]
	v_mfma_f32_16x16x4_f32 v[192:195], v25, v139, v[192:195]
	v_mfma_f32_16x16x4_f32 v[196:199], v25, v140, v[196:199]
	v_mfma_f32_16x16x4_f32 v[200:203], v25, v141, v[200:203]
	v_mfma_f32_16x16x4_f32 v[208:211], v25, v142, v[208:211]
	v_mfma_f32_16x16x4_f32 v[212:215], v25, v143, v[212:215]
	v_mfma_f32_16x16x4_f32 v[216:219], v25, v144, v[216:219]
	v_mfma_f32_16x16x4_f32 v[220:223], v25, v145, v[220:223]
	v_mfma_f32_16x16x4_f32 v[224:227], v25, v146, v[224:227]
	v_mfma_f32_16x16x4_f32 v[228:231], v25, v147, v[228:231]
	global_load_dwordx4 v[132:135], v5, s[8:9]
	global_load_dwordx4 v[136:139], v5, s[8:9] offset:256
	global_load_dwordx4 v[140:143], v5, s[8:9] offset:512
	global_load_dwordx4 v[144:147], v5, s[8:9] offset:768
	s_add_u32 s8, s8, 0x4000
	s_addc_u32 s9, s9, 0
	s_waitcnt vmcnt(4)
	v_mfma_f32_16x16x4_f32 v[160:163], v26, v30, v[160:163]
	v_mfma_f32_16x16x4_f32 v[164:167], v26, v31, v[164:167]
	v_mfma_f32_16x16x4_f32 v[168:171], v26, v32, v[168:171]
	v_mfma_f32_16x16x4_f32 v[176:179], v26, v33, v[176:179]
	v_mfma_f32_16x16x4_f32 v[180:183], v26, v34, v[180:183]
	v_mfma_f32_16x16x4_f32 v[184:187], v26, v35, v[184:187]
	v_mfma_f32_16x16x4_f32 v[188:191], v26, v36, v[188:191]
	v_mfma_f32_16x16x4_f32 v[192:195], v26, v37, v[192:195]
	v_mfma_f32_16x16x4_f32 v[196:199], v26, v38, v[196:199]
	v_mfma_f32_16x16x4_f32 v[200:203], v26, v39, v[200:203]
	v_mfma_f32_16x16x4_f32 v[208:211], v26, v40, v[208:211]
	v_mfma_f32_16x16x4_f32 v[212:215], v26, v41, v[212:215]
	v_mfma_f32_16x16x4_f32 v[216:219], v26, v42, v[216:219]
	v_mfma_f32_16x16x4_f32 v[220:223], v26, v43, v[220:223]
	v_mfma_f32_16x16x4_f32 v[224:227], v26, v44, v[224:227]
	v_mfma_f32_16x16x4_f32 v[228:231], v26, v45, v[228:231]
	global_load_dwordx4 v[30:33], v5, s[8:9]
	global_load_dwordx4 v[34:37], v5, s[8:9] offset:256
	global_load_dwordx4 v[38:41], v5, s[8:9] offset:512
	global_load_dwordx4 v[42:45], v5, s[8:9] offset:768
	s_add_u32 s8, s8, 0x4000
	s_addc_u32 s9, s9, 0
	s_waitcnt vmcnt(4)
	v_mfma_f32_16x16x4_f32 v[160:163], v27, v132, v[160:163]
	v_mfma_f32_16x16x4_f32 v[164:167], v27, v133, v[164:167]
	v_mfma_f32_16x16x4_f32 v[168:171], v27, v134, v[168:171]
	v_mfma_f32_16x16x4_f32 v[176:179], v27, v135, v[176:179]
	v_mfma_f32_16x16x4_f32 v[180:183], v27, v136, v[180:183]
	v_mfma_f32_16x16x4_f32 v[184:187], v27, v137, v[184:187]
	v_mfma_f32_16x16x4_f32 v[188:191], v27, v138, v[188:191]
	v_mfma_f32_16x16x4_f32 v[192:195], v27, v139, v[192:195]
	v_mfma_f32_16x16x4_f32 v[196:199], v27, v140, v[196:199]
	v_mfma_f32_16x16x4_f32 v[200:203], v27, v141, v[200:203]
	v_mfma_f32_16x16x4_f32 v[208:211], v27, v142, v[208:211]
	v_mfma_f32_16x16x4_f32 v[212:215], v27, v143, v[212:215]
	v_mfma_f32_16x16x4_f32 v[216:219], v27, v144, v[216:219]
	v_mfma_f32_16x16x4_f32 v[220:223], v27, v145, v[220:223]
	v_mfma_f32_16x16x4_f32 v[224:227], v27, v146, v[224:227]
	v_mfma_f32_16x16x4_f32 v[228:231], v27, v147, v[228:231]
	global_load_dwordx4 v[132:135], v5, s[8:9]
	global_load_dwordx4 v[136:139], v5, s[8:9] offset:256
	global_load_dwordx4 v[140:143], v5, s[8:9] offset:512
	global_load_dwordx4 v[144:147], v5, s[8:9] offset:768
	s_add_u32 s8, s8, 0x4000
	s_addc_u32 s9, s9, 0
	s_waitcnt vmcnt(4)
	v_mfma_f32_16x16x4_f32 v[160:163], v28, v30, v[160:163]
	v_mfma_f32_16x16x4_f32 v[164:167], v28, v31, v[164:167]
	v_mfma_f32_16x16x4_f32 v[168:171], v28, v32, v[168:171]
	v_mfma_f32_16x16x4_f32 v[176:179], v28, v33, v[176:179]
	v_mfma_f32_16x16x4_f32 v[180:183], v28, v34, v[180:183]
	v_mfma_f32_16x16x4_f32 v[184:187], v28, v35, v[184:187]
	v_mfma_f32_16x16x4_f32 v[188:191], v28, v36, v[188:191]
	v_mfma_f32_16x16x4_f32 v[192:195], v28, v37, v[192:195]
	v_mfma_f32_16x16x4_f32 v[196:199], v28, v38, v[196:199]
	v_mfma_f32_16x16x4_f32 v[200:203], v28, v39, v[200:203]
	v_mfma_f32_16x16x4_f32 v[208:211], v28, v40, v[208:211]
	v_mfma_f32_16x16x4_f32 v[212:215], v28, v41, v[212:215]
	v_mfma_f32_16x16x4_f32 v[216:219], v28, v42, v[216:219]
	v_mfma_f32_16x16x4_f32 v[220:223], v28, v43, v[220:223]
	v_mfma_f32_16x16x4_f32 v[224:227], v28, v44, v[224:227]
	v_mfma_f32_16x16x4_f32 v[228:231], v28, v45, v[228:231]
	s_waitcnt vmcnt(0)
	v_mfma_f32_16x16x4_f32 v[160:163], v29, v132, v[160:163]
	v_mfma_f32_16x16x4_f32 v[164:167], v29, v133, v[164:167]
	v_mfma_f32_16x16x4_f32 v[168:171], v29, v134, v[168:171]
	v_mfma_f32_16x16x4_f32 v[176:179], v29, v135, v[176:179]
	v_mfma_f32_16x16x4_f32 v[180:183], v29, v136, v[180:183]
	v_mfma_f32_16x16x4_f32 v[184:187], v29, v137, v[184:187]
	v_mfma_f32_16x16x4_f32 v[188:191], v29, v138, v[188:191]
	v_mfma_f32_16x16x4_f32 v[192:195], v29, v139, v[192:195]
	v_mfma_f32_16x16x4_f32 v[196:199], v29, v140, v[196:199]
	v_mfma_f32_16x16x4_f32 v[200:203], v29, v141, v[200:203]
	v_mfma_f32_16x16x4_f32 v[208:211], v29, v142, v[208:211]
	v_mfma_f32_16x16x4_f32 v[212:215], v29, v143, v[212:215]
	v_mfma_f32_16x16x4_f32 v[216:219], v29, v144, v[216:219]
	v_mfma_f32_16x16x4_f32 v[220:223], v29, v145, v[220:223]
	v_mfma_f32_16x16x4_f32 v[224:227], v29, v146, v[224:227]
	v_mfma_f32_16x16x4_f32 v[228:231], v29, v147, v[228:231]
	s_nop 7
	s_nop 3
	v_lshl_add_u32 v13, v3, 2, v13
	v_mov_b32_e32 v12, 0xc4ffe000
	v_add_u32_e32 v10, 0, v13
	v_cvt_f32_u32_e32 v10, v10
	v_div_scale_f32 v11, vcc, v12, v12, v10
	v_rcp_f32_e32 v148, v11
	s_nop 0
	v_fma_f32 v158, -v11, v148, 1.0
	v_fmac_f32_e32 v148, v158, v148
	v_div_scale_f32 v158, vcc, v10, v12, v10
	v_mul_f32_e32 v159, v158, v148
	v_fma_f32 v172, -v11, v159, v158
	v_fmac_f32_e32 v159, v172, v148
	v_fma_f32 v158, -v11, v159, v158
	v_div_fmas_f32 v158, v158, v148, v159
	v_div_fixup_f32 v6, v158, v12, v10
	v_add_u32_e32 v10, 1, v13
	v_cvt_f32_u32_e32 v10, v10
	v_div_scale_f32 v11, vcc, v12, v12, v10
	v_rcp_f32_e32 v148, v11
	s_nop 0
	v_fma_f32 v158, -v11, v148, 1.0
	v_fmac_f32_e32 v148, v158, v148
	v_div_scale_f32 v158, vcc, v10, v12, v10
	v_mul_f32_e32 v159, v158, v148
	v_fma_f32 v172, -v11, v159, v158
	v_fmac_f32_e32 v159, v172, v148
	v_fma_f32 v158, -v11, v159, v158
	v_div_fmas_f32 v158, v158, v148, v159
	v_div_fixup_f32 v7, v158, v12, v10
	v_add_u32_e32 v10, 2, v13
	v_cvt_f32_u32_e32 v10, v10
	v_div_scale_f32 v11, vcc, v12, v12, v10
	v_rcp_f32_e32 v148, v11
	s_nop 0
	v_fma_f32 v158, -v11, v148, 1.0
	v_fmac_f32_e32 v148, v158, v148
	v_div_scale_f32 v158, vcc, v10, v12, v10
	v_mul_f32_e32 v159, v158, v148
	v_fma_f32 v172, -v11, v159, v158
	v_fmac_f32_e32 v159, v172, v148
	v_fma_f32 v158, -v11, v159, v158
	v_div_fmas_f32 v158, v158, v148, v159
	v_div_fixup_f32 v8, v158, v12, v10
	v_add_u32_e32 v10, 3, v13
	v_cvt_f32_u32_e32 v10, v10
	v_div_scale_f32 v11, vcc, v12, v12, v10
	v_rcp_f32_e32 v148, v11
	s_nop 0
	v_fma_f32 v158, -v11, v148, 1.0
	v_fmac_f32_e32 v148, v158, v148
	v_div_scale_f32 v158, vcc, v10, v12, v10
	v_mul_f32_e32 v159, v158, v148
	v_fma_f32 v172, -v11, v159, v158
	v_fmac_f32_e32 v159, v172, v148
	v_fma_f32 v158, -v11, v159, v158
	v_div_fmas_f32 v158, v158, v148, v159
	v_div_fixup_f32 v9, v158, v12, v10
	v_lshlrev_b32_e32 v10, 8, v205
	v_lshl_add_u32 v10, v2, 2, v10
	v_lshlrev_b32_e32 v11, 13, v10
	v_lshl_add_u32 v11, v3, 4, v11
	v_lshlrev_b32_e32 v10, 2, v2
	v_mov_b32_e32 v173, 0x40447cbd
	v_mov_b32_e32 v148, v10
	v_cvt_f32_u32_e32 v148, v148
	v_fmamk_f32 v148, v148, 0x3d4541ff, v173
	v_mul_f32_e32 v158, v6, v148
	v_mul_f32_e32 v158, 0x3fb8aa3b, v158
	v_exp_f32_e32 v158, v158
	v_mul_f32_e32 v159, v7, v148
	v_mul_f32_e32 v159, 0x3fb8aa3b, v159
	v_exp_f32_e32 v159, v159
	v_mul_f32_e32 v172, v8, v148
	v_mul_f32_e32 v172, 0x3fb8aa3b, v172
	v_exp_f32_e32 v172, v172
	v_mul_f32_e32 v204, v9, v148
	v_mul_f32_e32 v204, 0x3fb8aa3b, v204
	v_exp_f32_e32 v204, v204
	s_nop 0
	v_mul_f32_e32 v160, v158, v160
	v_mul_f32_e32 v161, v159, v161
	v_mul_f32_e32 v162, v172, v162
	v_mul_f32_e32 v163, v204, v163
	global_store_dwordx4 v11, v[160:163], s[4:5]
	v_add_u32_e32 v148, 1, v10
	v_cvt_f32_u32_e32 v148, v148
	v_fmamk_f32 v148, v148, 0x3d4541ff, v173
	v_mul_f32_e32 v158, v6, v148
	v_mul_f32_e32 v158, 0x3fb8aa3b, v158
	v_exp_f32_e32 v158, v158
	v_mul_f32_e32 v159, v7, v148
	v_mul_f32_e32 v159, 0x3fb8aa3b, v159
	v_exp_f32_e32 v159, v159
	v_mul_f32_e32 v172, v8, v148
	v_mul_f32_e32 v172, 0x3fb8aa3b, v172
	v_exp_f32_e32 v172, v172
	v_mul_f32_e32 v204, v9, v148
	v_mul_f32_e32 v204, 0x3fb8aa3b, v204
	v_exp_f32_e32 v204, v204
	s_nop 0
	v_mul_f32_e32 v164, v158, v164
	v_mul_f32_e32 v165, v159, v165
	v_mul_f32_e32 v166, v172, v166
	v_mul_f32_e32 v167, v204, v167
	v_add_u32_e32 v205, 0x2000, v11
	global_store_dwordx4 v205, v[164:167], s[4:5]
	v_add_u32_e32 v148, 2, v10
	v_cvt_f32_u32_e32 v148, v148
	v_fmamk_f32 v148, v148, 0x3d4541ff, v173
	v_mul_f32_e32 v158, v6, v148
	v_mul_f32_e32 v158, 0x3fb8aa3b, v158
	v_exp_f32_e32 v158, v158
	v_mul_f32_e32 v159, v7, v148
	v_mul_f32_e32 v159, 0x3fb8aa3b, v159
	v_exp_f32_e32 v159, v159
	v_mul_f32_e32 v172, v8, v148
	v_mul_f32_e32 v172, 0x3fb8aa3b, v172
	v_exp_f32_e32 v172, v172
	v_mul_f32_e32 v204, v9, v148
	v_mul_f32_e32 v204, 0x3fb8aa3b, v204
	v_exp_f32_e32 v204, v204
	s_nop 0
	v_mul_f32_e32 v168, v158, v168
	v_mul_f32_e32 v169, v159, v169
	v_mul_f32_e32 v170, v172, v170
	v_mul_f32_e32 v171, v204, v171
	v_add_u32_e32 v205, 0x4000, v11
	global_store_dwordx4 v205, v[168:171], s[4:5]
	v_add_u32_e32 v148, 3, v10
	v_cvt_f32_u32_e32 v148, v148
	v_fmamk_f32 v148, v148, 0x3d4541ff, v173
	v_mul_f32_e32 v158, v6, v148
	v_mul_f32_e32 v158, 0x3fb8aa3b, v158
	v_exp_f32_e32 v158, v158
	v_mul_f32_e32 v159, v7, v148
	v_mul_f32_e32 v159, 0x3fb8aa3b, v159
	v_exp_f32_e32 v159, v159
	v_mul_f32_e32 v172, v8, v148
	v_mul_f32_e32 v172, 0x3fb8aa3b, v172
	v_exp_f32_e32 v172, v172
	v_mul_f32_e32 v204, v9, v148
	v_mul_f32_e32 v204, 0x3fb8aa3b, v204
	v_exp_f32_e32 v204, v204
	s_nop 0
	v_mul_f32_e32 v176, v158, v176
	v_mul_f32_e32 v177, v159, v177
	v_mul_f32_e32 v178, v172, v178
	v_mul_f32_e32 v179, v204, v179
	v_add_u32_e32 v205, 0x6000, v11
	global_store_dwordx4 v205, v[176:179], s[4:5]
	v_add_u32_e32 v148, 64, v10
	v_cvt_f32_u32_e32 v148, v148
	v_fmamk_f32 v148, v148, 0x3d4541ff, v173
	v_mul_f32_e32 v158, v6, v148
	v_mul_f32_e32 v158, 0x3fb8aa3b, v158
	v_exp_f32_e32 v158, v158
	v_mul_f32_e32 v159, v7, v148
	v_mul_f32_e32 v159, 0x3fb8aa3b, v159
	v_exp_f32_e32 v159, v159
	v_mul_f32_e32 v172, v8, v148
	v_mul_f32_e32 v172, 0x3fb8aa3b, v172
	v_exp_f32_e32 v172, v172
	v_mul_f32_e32 v204, v9, v148
	v_mul_f32_e32 v204, 0x3fb8aa3b, v204
	v_exp_f32_e32 v204, v204
	s_nop 0
	v_mul_f32_e32 v180, v158, v180
	v_mul_f32_e32 v181, v159, v181
	v_mul_f32_e32 v182, v172, v182
	v_mul_f32_e32 v183, v204, v183
	v_add_u32_e32 v205, 0x80000, v11
	global_store_dwordx4 v205, v[180:183], s[4:5]
	v_add_u32_e32 v148, 65, v10
	v_cvt_f32_u32_e32 v148, v148
	v_fmamk_f32 v148, v148, 0x3d4541ff, v173
	v_mul_f32_e32 v158, v6, v148
	v_mul_f32_e32 v158, 0x3fb8aa3b, v158
	v_exp_f32_e32 v158, v158
	v_mul_f32_e32 v159, v7, v148
	v_mul_f32_e32 v159, 0x3fb8aa3b, v159
	v_exp_f32_e32 v159, v159
	v_mul_f32_e32 v172, v8, v148
	v_mul_f32_e32 v172, 0x3fb8aa3b, v172
	v_exp_f32_e32 v172, v172
	v_mul_f32_e32 v204, v9, v148
	v_mul_f32_e32 v204, 0x3fb8aa3b, v204
	v_exp_f32_e32 v204, v204
	s_nop 0
	v_mul_f32_e32 v184, v158, v184
	v_mul_f32_e32 v185, v159, v185
	v_mul_f32_e32 v186, v172, v186
	v_mul_f32_e32 v187, v204, v187
	v_add_u32_e32 v205, 0x82000, v11
	global_store_dwordx4 v205, v[184:187], s[4:5]
	v_add_u32_e32 v148, 66, v10
	v_cvt_f32_u32_e32 v148, v148
	v_fmamk_f32 v148, v148, 0x3d4541ff, v173
	v_mul_f32_e32 v158, v6, v148
	v_mul_f32_e32 v158, 0x3fb8aa3b, v158
	v_exp_f32_e32 v158, v158
	v_mul_f32_e32 v159, v7, v148
	v_mul_f32_e32 v159, 0x3fb8aa3b, v159
	v_exp_f32_e32 v159, v159
	v_mul_f32_e32 v172, v8, v148
	v_mul_f32_e32 v172, 0x3fb8aa3b, v172
	v_exp_f32_e32 v172, v172
	v_mul_f32_e32 v204, v9, v148
	v_mul_f32_e32 v204, 0x3fb8aa3b, v204
	v_exp_f32_e32 v204, v204
	s_nop 0
	v_mul_f32_e32 v188, v158, v188
	v_mul_f32_e32 v189, v159, v189
	v_mul_f32_e32 v190, v172, v190
	v_mul_f32_e32 v191, v204, v191
	v_add_u32_e32 v205, 0x84000, v11
	global_store_dwordx4 v205, v[188:191], s[4:5]
	v_add_u32_e32 v148, 67, v10
	v_cvt_f32_u32_e32 v148, v148
	v_fmamk_f32 v148, v148, 0x3d4541ff, v173
	v_mul_f32_e32 v158, v6, v148
	v_mul_f32_e32 v158, 0x3fb8aa3b, v158
	v_exp_f32_e32 v158, v158
	v_mul_f32_e32 v159, v7, v148
	v_mul_f32_e32 v159, 0x3fb8aa3b, v159
	v_exp_f32_e32 v159, v159
	v_mul_f32_e32 v172, v8, v148
	v_mul_f32_e32 v172, 0x3fb8aa3b, v172
	v_exp_f32_e32 v172, v172
	v_mul_f32_e32 v204, v9, v148
	v_mul_f32_e32 v204, 0x3fb8aa3b, v204
	v_exp_f32_e32 v204, v204
	s_nop 0
	v_mul_f32_e32 v192, v158, v192
	v_mul_f32_e32 v193, v159, v193
	v_mul_f32_e32 v194, v172, v194
	v_mul_f32_e32 v195, v204, v195
	v_add_u32_e32 v205, 0x86000, v11
	global_store_dwordx4 v205, v[192:195], s[4:5]
	v_add_u32_e32 v148, 128, v10
	v_cvt_f32_u32_e32 v148, v148
	v_fmamk_f32 v148, v148, 0x3d4541ff, v173
	v_mul_f32_e32 v158, v6, v148
	v_mul_f32_e32 v158, 0x3fb8aa3b, v158
	v_exp_f32_e32 v158, v158
	v_mul_f32_e32 v159, v7, v148
	v_mul_f32_e32 v159, 0x3fb8aa3b, v159
	v_exp_f32_e32 v159, v159
	v_mul_f32_e32 v172, v8, v148
	v_mul_f32_e32 v172, 0x3fb8aa3b, v172
	v_exp_f32_e32 v172, v172
	v_mul_f32_e32 v204, v9, v148
	v_mul_f32_e32 v204, 0x3fb8aa3b, v204
	v_exp_f32_e32 v204, v204
	s_nop 0
	v_mul_f32_e32 v196, v158, v196
	v_mul_f32_e32 v197, v159, v197
	v_mul_f32_e32 v198, v172, v198
	v_mul_f32_e32 v199, v204, v199
	v_add_u32_e32 v205, 0x100000, v11
	global_store_dwordx4 v205, v[196:199], s[4:5]
	v_add_u32_e32 v148, 129, v10
	v_cvt_f32_u32_e32 v148, v148
	v_fmamk_f32 v148, v148, 0x3d4541ff, v173
	v_mul_f32_e32 v158, v6, v148
	v_mul_f32_e32 v158, 0x3fb8aa3b, v158
	v_exp_f32_e32 v158, v158
	v_mul_f32_e32 v159, v7, v148
	v_mul_f32_e32 v159, 0x3fb8aa3b, v159
	v_exp_f32_e32 v159, v159
	v_mul_f32_e32 v172, v8, v148
	v_mul_f32_e32 v172, 0x3fb8aa3b, v172
	v_exp_f32_e32 v172, v172
	v_mul_f32_e32 v204, v9, v148
	v_mul_f32_e32 v204, 0x3fb8aa3b, v204
	v_exp_f32_e32 v204, v204
	s_nop 0
	v_mul_f32_e32 v200, v158, v200
	v_mul_f32_e32 v201, v159, v201
	v_mul_f32_e32 v202, v172, v202
	v_mul_f32_e32 v203, v204, v203
	v_add_u32_e32 v205, 0x102000, v11
	global_store_dwordx4 v205, v[200:203], s[4:5]
	v_add_u32_e32 v148, 130, v10
	v_cvt_f32_u32_e32 v148, v148
	v_fmamk_f32 v148, v148, 0x3d4541ff, v173
	v_mul_f32_e32 v158, v6, v148
	v_mul_f32_e32 v158, 0x3fb8aa3b, v158
	v_exp_f32_e32 v158, v158
	v_mul_f32_e32 v159, v7, v148
	v_mul_f32_e32 v159, 0x3fb8aa3b, v159
	v_exp_f32_e32 v159, v159
	v_mul_f32_e32 v172, v8, v148
	v_mul_f32_e32 v172, 0x3fb8aa3b, v172
	v_exp_f32_e32 v172, v172
	v_mul_f32_e32 v204, v9, v148
	v_mul_f32_e32 v204, 0x3fb8aa3b, v204
	v_exp_f32_e32 v204, v204
	s_nop 0
	v_mul_f32_e32 v208, v158, v208
	v_mul_f32_e32 v209, v159, v209
	v_mul_f32_e32 v210, v172, v210
	v_mul_f32_e32 v211, v204, v211
	v_add_u32_e32 v205, 0x104000, v11
	global_store_dwordx4 v205, v[208:211], s[4:5]
	v_add_u32_e32 v148, 131, v10
	v_cvt_f32_u32_e32 v148, v148
	v_fmamk_f32 v148, v148, 0x3d4541ff, v173
	v_mul_f32_e32 v158, v6, v148
	v_mul_f32_e32 v158, 0x3fb8aa3b, v158
	v_exp_f32_e32 v158, v158
	v_mul_f32_e32 v159, v7, v148
	v_mul_f32_e32 v159, 0x3fb8aa3b, v159
	v_exp_f32_e32 v159, v159
	v_mul_f32_e32 v172, v8, v148
	v_mul_f32_e32 v172, 0x3fb8aa3b, v172
	v_exp_f32_e32 v172, v172
	v_mul_f32_e32 v204, v9, v148
	v_mul_f32_e32 v204, 0x3fb8aa3b, v204
	v_exp_f32_e32 v204, v204
	s_nop 0
	v_mul_f32_e32 v212, v158, v212
	v_mul_f32_e32 v213, v159, v213
	v_mul_f32_e32 v214, v172, v214
	v_mul_f32_e32 v215, v204, v215
	v_add_u32_e32 v205, 0x106000, v11
	global_store_dwordx4 v205, v[212:215], s[4:5]
	v_add_u32_e32 v148, 192, v10
	v_cvt_f32_u32_e32 v148, v148
	v_fmamk_f32 v148, v148, 0x3d4541ff, v173
	v_mul_f32_e32 v158, v6, v148
	v_mul_f32_e32 v158, 0x3fb8aa3b, v158
	v_exp_f32_e32 v158, v158
	v_mul_f32_e32 v159, v7, v148
	v_mul_f32_e32 v159, 0x3fb8aa3b, v159
	v_exp_f32_e32 v159, v159
	v_mul_f32_e32 v172, v8, v148
	v_mul_f32_e32 v172, 0x3fb8aa3b, v172
	v_exp_f32_e32 v172, v172
	v_mul_f32_e32 v204, v9, v148
	v_mul_f32_e32 v204, 0x3fb8aa3b, v204
	v_exp_f32_e32 v204, v204
	s_nop 0
	v_mul_f32_e32 v216, v158, v216
	v_mul_f32_e32 v217, v159, v217
	v_mul_f32_e32 v218, v172, v218
	v_mul_f32_e32 v219, v204, v219
	v_add_u32_e32 v205, 0x180000, v11
	global_store_dwordx4 v205, v[216:219], s[4:5]
	v_add_u32_e32 v148, 193, v10
	v_cvt_f32_u32_e32 v148, v148
	v_fmamk_f32 v148, v148, 0x3d4541ff, v173
	v_mul_f32_e32 v158, v6, v148
	v_mul_f32_e32 v158, 0x3fb8aa3b, v158
	v_exp_f32_e32 v158, v158
	v_mul_f32_e32 v159, v7, v148
	v_mul_f32_e32 v159, 0x3fb8aa3b, v159
	v_exp_f32_e32 v159, v159
	v_mul_f32_e32 v172, v8, v148
	v_mul_f32_e32 v172, 0x3fb8aa3b, v172
	v_exp_f32_e32 v172, v172
	v_mul_f32_e32 v204, v9, v148
	v_mul_f32_e32 v204, 0x3fb8aa3b, v204
	v_exp_f32_e32 v204, v204
	s_nop 0
	v_mul_f32_e32 v220, v158, v220
	v_mul_f32_e32 v221, v159, v221
	v_mul_f32_e32 v222, v172, v222
	v_mul_f32_e32 v223, v204, v223
	v_add_u32_e32 v205, 0x182000, v11
	global_store_dwordx4 v205, v[220:223], s[4:5]
	v_add_u32_e32 v148, 194, v10
	v_cvt_f32_u32_e32 v148, v148
	v_fmamk_f32 v148, v148, 0x3d4541ff, v173
	v_mul_f32_e32 v158, v6, v148
	v_mul_f32_e32 v158, 0x3fb8aa3b, v158
	v_exp_f32_e32 v158, v158
	v_mul_f32_e32 v159, v7, v148
	v_mul_f32_e32 v159, 0x3fb8aa3b, v159
	v_exp_f32_e32 v159, v159
	v_mul_f32_e32 v172, v8, v148
	v_mul_f32_e32 v172, 0x3fb8aa3b, v172
	v_exp_f32_e32 v172, v172
	v_mul_f32_e32 v204, v9, v148
	v_mul_f32_e32 v204, 0x3fb8aa3b, v204
	v_exp_f32_e32 v204, v204
	s_nop 0
	v_mul_f32_e32 v224, v158, v224
	v_mul_f32_e32 v225, v159, v225
	v_mul_f32_e32 v226, v172, v226
	v_mul_f32_e32 v227, v204, v227
	v_add_u32_e32 v205, 0x184000, v11
	global_store_dwordx4 v205, v[224:227], s[4:5]
	v_add_u32_e32 v148, 195, v10
	v_cvt_f32_u32_e32 v148, v148
	v_fmamk_f32 v148, v148, 0x3d4541ff, v173
	v_mul_f32_e32 v158, v6, v148
	v_mul_f32_e32 v158, 0x3fb8aa3b, v158
	v_exp_f32_e32 v158, v158
	v_mul_f32_e32 v159, v7, v148
	v_mul_f32_e32 v159, 0x3fb8aa3b, v159
	v_exp_f32_e32 v159, v159
	v_mul_f32_e32 v172, v8, v148
	v_mul_f32_e32 v172, 0x3fb8aa3b, v172
	v_exp_f32_e32 v172, v172
	v_mul_f32_e32 v204, v9, v148
	v_mul_f32_e32 v204, 0x3fb8aa3b, v204
	v_exp_f32_e32 v204, v204
	s_nop 0
	v_mul_f32_e32 v228, v158, v228
	v_mul_f32_e32 v229, v159, v229
	v_mul_f32_e32 v230, v172, v230
	v_mul_f32_e32 v231, v204, v231
	v_add_u32_e32 v205, 0x186000, v11
	global_store_dwordx4 v205, v[228:231], s[4:5]
	s_barrier
	s_mov_b64 s[0:1], 0
